# speedup vs baseline: 1.1993x; 1.0078x over previous
.LBB0_454:
	s_ashr_i32 s27, s26, 31
	s_lshl_b32 s25, s24, 9
	s_and_b32 s25, s25, 0x600
	s_lshl_b64 s[28:29], s[26:27], 19
	s_add_u32 s27, s6, s28
	s_addc_u32 s29, s7, s29
	s_add_u32 s28, s27, s25
	s_addc_u32 s29, s29, 0
	ds_read_b128 v[0:3], v93
	ds_read_b128 v[4:7], v93 offset:1024
	ds_read_b128 v[8:11], v93 offset:2048
	ds_read_b128 v[12:15], v93 offset:3072
	s_and_b64 s[30:31], s[38:39], exec
	s_cselect_b32 s45, s29, s41
	s_cselect_b32 s44, s28, s40
	s_ashr_i32 s25, s24, 31
	s_lshl_b64 s[30:31], s[24:25], 17
	s_add_u32 s30, s12, s30
	s_addc_u32 s31, s13, s31
	s_and_b64 s[38:39], s[38:39], exec
	s_cselect_b32 s39, s31, s43
	s_cselect_b32 s38, s30, s42
	s_add_u32 s62, s40, 0x40080
	s_addc_u32 s63, s41, 0
	s_mov_b32 m0, s59
	v_lshl_add_u64 v[48:49], s[62:63], 0, v[86:87]
	ds_read_b128 v[16:19], v91
	ds_read_b128 v[20:23], v91 offset:1024
	ds_read_b128 v[24:27], v91 offset:2048
	ds_read_b128 v[28:31], v91 offset:3072
	ds_read_b128 v[32:35], v91 offset:4096
	ds_read_b128 v[36:39], v91 offset:5120
	ds_read_b128 v[40:43], v91 offset:6144
	ds_read_b128 v[44:47], v91 offset:7168
	global_load_lds_dwordx4 v[48:49], off
	v_lshl_add_u64 v[48:49], s[62:63], 0, v[82:83]
	s_mov_b32 m0, s60
	s_nop 0
	global_load_lds_dwordx4 v[48:49], off
	s_waitcnt lgkmcnt(8)
	s_barrier
	s_waitcnt lgkmcnt(0)
	s_setprio 1
	s_waitcnt lgkmcnt(0)
	v_mfma_f32_16x16x32_bf16 v[48:51], v[0:3], v[16:19], 0
	v_mfma_f32_16x16x32_bf16 v[52:55], v[8:11], v[16:19], 0
	v_mfma_f32_16x16x32_bf16 v[56:59], v[0:3], v[24:27], 0
	v_mfma_f32_16x16x32_bf16 v[60:63], v[8:11], v[24:27], 0
	v_mfma_f32_16x16x32_bf16 v[64:67], v[0:3], v[32:35], 0
	v_mfma_f32_16x16x32_bf16 v[68:71], v[8:11], v[32:35], 0
	v_mfma_f32_16x16x32_bf16 v[72:75], v[0:3], v[40:43], 0
	v_mfma_f32_16x16x32_bf16 v[76:79], v[8:11], v[40:43], 0
	v_mfma_f32_16x16x32_bf16 v[48:51], v[4:7], v[20:23], v[48:51]
	v_mfma_f32_16x16x32_bf16 v[52:55], v[12:15], v[20:23], v[52:55]
	v_mfma_f32_16x16x32_bf16 v[56:59], v[4:7], v[28:31], v[56:59]
	v_mfma_f32_16x16x32_bf16 v[60:63], v[12:15], v[28:31], v[60:63]
	v_mfma_f32_16x16x32_bf16 v[64:67], v[4:7], v[36:39], v[64:67]
	v_mfma_f32_16x16x32_bf16 v[68:71], v[12:15], v[36:39], v[68:71]
	v_mfma_f32_16x16x32_bf16 v[72:75], v[4:7], v[44:47], v[72:75]
	v_mfma_f32_16x16x32_bf16 v[76:79], v[12:15], v[44:47], v[76:79]
	s_setprio 0
	s_barrier
	v_lshl_add_u64 v[212:213], s[42:43], 0, v[84:85]
	s_mov_b32 m0, s35
	v_lshl_add_u64 v[114:115], v[212:213], 0, s[18:19]
	v_lshl_add_u64 v[214:215], s[42:43], 0, v[80:81]
	ds_read_b128 v[98:101], v94
	ds_read_b128 v[102:105], v94 offset:1024
	ds_read_b128 v[106:109], v94 offset:2048
	ds_read_b128 v[110:113], v94 offset:3072
	global_load_lds_dwordx4 v[114:115], off
	v_lshl_add_u64 v[114:115], v[214:215], 0, s[18:19]
	s_mov_b32 m0, s47
	s_nop 0
	global_load_lds_dwordx4 v[114:115], off
	s_barrier
	s_waitcnt lgkmcnt(0)
	s_setprio 1
	s_waitcnt lgkmcnt(0)
	v_mfma_f32_16x16x32_bf16 v[114:117], v[98:101], v[16:19], 0
	v_mfma_f32_16x16x32_bf16 v[16:19], v[106:109], v[16:19], 0
	v_mfma_f32_16x16x32_bf16 v[114:117], v[102:105], v[20:23], v[114:117]
	v_mfma_f32_16x16x32_bf16 v[16:19], v[110:113], v[20:23], v[16:19]
	v_mfma_f32_16x16x32_bf16 v[20:23], v[98:101], v[24:27], 0
	v_mfma_f32_16x16x32_bf16 v[24:27], v[106:109], v[24:27], 0
	v_mfma_f32_16x16x32_bf16 v[20:23], v[102:105], v[28:31], v[20:23]
	v_mfma_f32_16x16x32_bf16 v[24:27], v[110:113], v[28:31], v[24:27]
	v_mfma_f32_16x16x32_bf16 v[28:31], v[98:101], v[32:35], 0
	v_mfma_f32_16x16x32_bf16 v[32:35], v[106:109], v[32:35], 0
	v_mfma_f32_16x16x32_bf16 v[28:31], v[102:105], v[36:39], v[28:31]
	v_mfma_f32_16x16x32_bf16 v[32:35], v[110:113], v[36:39], v[32:35]
	v_mfma_f32_16x16x32_bf16 v[36:39], v[98:101], v[40:43], 0
	v_mfma_f32_16x16x32_bf16 v[40:43], v[106:109], v[40:43], 0
	v_mfma_f32_16x16x32_bf16 v[36:39], v[102:105], v[44:47], v[36:39]
	v_mfma_f32_16x16x32_bf16 v[40:43], v[110:113], v[44:47], v[40:43]
	s_setprio 0
	v_lshl_add_u64 v[216:217], s[40:41], 0, v[86:87]
	s_mov_b32 m0, s46
	v_lshl_add_u64 v[148:149], v[216:217], 0, s[18:19]
	v_lshl_add_u64 v[218:219], s[40:41], 0, v[82:83]
	s_barrier
	ds_read_b128 v[44:47], v91 offset:16384
	ds_read_b128 v[118:121], v91 offset:17408
	ds_read_b128 v[122:125], v91 offset:18432
	ds_read_b128 v[126:129], v91 offset:19456
	ds_read_b128 v[130:133], v91 offset:20480
	ds_read_b128 v[134:137], v91 offset:21504
	ds_read_b128 v[138:141], v91 offset:22528
	ds_read_b128 v[142:145], v91 offset:23552
	global_load_lds_dwordx4 v[148:149], off
	v_lshl_add_u64 v[148:149], v[218:219], 0, s[18:19]
	s_mov_b32 m0, s48
	s_nop 0
	global_load_lds_dwordx4 v[148:149], off
	s_barrier
	s_waitcnt lgkmcnt(0)
	s_setprio 1
	s_waitcnt lgkmcnt(0)
	v_mfma_f32_16x16x32_bf16 v[148:151], v[0:3], v[44:47], 0
	v_mfma_f32_16x16x32_bf16 v[156:159], v[0:3], v[122:125], 0
	v_mfma_f32_16x16x32_bf16 v[164:167], v[0:3], v[130:133], 0
	v_mfma_f32_16x16x32_bf16 v[0:3], v[0:3], v[138:141], 0
	v_mfma_f32_16x16x32_bf16 v[148:151], v[4:7], v[118:121], v[148:151]
	v_mfma_f32_16x16x32_bf16 v[152:155], v[8:11], v[44:47], 0
	v_mfma_f32_16x16x32_bf16 v[156:159], v[4:7], v[126:129], v[156:159]
	v_mfma_f32_16x16x32_bf16 v[160:163], v[8:11], v[122:125], 0
	v_mfma_f32_16x16x32_bf16 v[164:167], v[4:7], v[134:137], v[164:167]
	v_mfma_f32_16x16x32_bf16 v[168:171], v[8:11], v[130:133], 0
	v_mfma_f32_16x16x32_bf16 v[0:3], v[4:7], v[142:145], v[0:3]
	v_mfma_f32_16x16x32_bf16 v[4:7], v[8:11], v[138:141], 0
	v_mfma_f32_16x16x32_bf16 v[152:155], v[12:15], v[118:121], v[152:155]
	v_mfma_f32_16x16x32_bf16 v[160:163], v[12:15], v[126:129], v[160:163]
	v_mfma_f32_16x16x32_bf16 v[168:171], v[12:15], v[134:137], v[168:171]
	v_mfma_f32_16x16x32_bf16 v[4:7], v[12:15], v[142:145], v[4:7]
	s_setprio 0
	s_barrier
	s_add_u32 s62, s42, 0x10100
	s_addc_u32 s63, s43, 0
	s_mov_b32 m0, s49
	v_lshl_add_u64 v[8:9], s[62:63], 0, v[84:85]
	global_load_lds_dwordx4 v[8:9], off
	v_lshl_add_u64 v[8:9], s[62:63], 0, v[80:81]
	s_mov_b32 m0, s50
	s_nop 0
	global_load_lds_dwordx4 v[8:9], off
	s_waitcnt vmcnt(6)
	s_barrier
	s_setprio 1
	v_mfma_f32_16x16x32_bf16 v[8:11], v[98:101], v[44:47], 0
	v_mfma_f32_16x16x32_bf16 v[12:15], v[106:109], v[44:47], 0
	v_mfma_f32_16x16x32_bf16 v[8:11], v[102:105], v[118:121], v[8:11]
	v_mfma_f32_16x16x32_bf16 v[12:15], v[110:113], v[118:121], v[12:15]
	v_mfma_f32_16x16x32_bf16 v[44:47], v[98:101], v[122:125], 0
	v_mfma_f32_16x16x32_bf16 v[118:121], v[106:109], v[122:125], 0
	v_mfma_f32_16x16x32_bf16 v[122:125], v[98:101], v[130:133], 0
	v_mfma_f32_16x16x32_bf16 v[98:101], v[98:101], v[138:141], 0
	v_mfma_f32_16x16x32_bf16 v[44:47], v[102:105], v[126:129], v[44:47]
	v_mfma_f32_16x16x32_bf16 v[118:121], v[110:113], v[126:129], v[118:121]
	v_mfma_f32_16x16x32_bf16 v[122:125], v[102:105], v[134:137], v[122:125]
	v_mfma_f32_16x16x32_bf16 v[126:129], v[106:109], v[130:133], 0
	v_mfma_f32_16x16x32_bf16 v[98:101], v[102:105], v[142:145], v[98:101]
	v_mfma_f32_16x16x32_bf16 v[102:105], v[106:109], v[138:141], 0
	v_mfma_f32_16x16x32_bf16 v[126:129], v[110:113], v[134:137], v[126:129]
	v_mfma_f32_16x16x32_bf16 v[102:105], v[110:113], v[142:145], v[102:105]
	s_setprio 0
	s_barrier
	ds_read_b128 v[106:109], v95
	ds_read_b128 v[110:113], v95 offset:1024
	ds_read_b128 v[130:133], v95 offset:2048
	ds_read_b128 v[134:137], v95 offset:3072
	s_add_u32 s62, s40, 0x40100
	s_addc_u32 s63, s41, 0
	s_mov_b32 m0, s51
	v_lshl_add_u64 v[196:197], s[62:63], 0, v[86:87]
	ds_read_b128 v[138:141], v91 offset:32768
	ds_read_b128 v[142:145], v91 offset:33792
	ds_read_b128 v[172:175], v91 offset:34816
	ds_read_b128 v[176:179], v91 offset:35840
	ds_read_b128 v[180:183], v91 offset:36864
	ds_read_b128 v[184:187], v91 offset:37888
	ds_read_b128 v[188:191], v91 offset:38912
	ds_read_b128 v[192:195], v91 offset:39936
	global_load_lds_dwordx4 v[196:197], off
	v_lshl_add_u64 v[196:197], s[62:63], 0, v[82:83]
	s_mov_b32 m0, s52
	s_nop 0
	global_load_lds_dwordx4 v[196:197], off
	s_waitcnt lgkmcnt(8)
	s_barrier
	s_waitcnt lgkmcnt(0)
	s_setprio 1
	s_waitcnt lgkmcnt(0)
	v_mfma_f32_16x16x32_bf16 v[48:51], v[106:109], v[138:141], v[48:51]
	v_mfma_f32_16x16x32_bf16 v[52:55], v[130:133], v[138:141], v[52:55]
	v_mfma_f32_16x16x32_bf16 v[56:59], v[106:109], v[172:175], v[56:59]
	v_mfma_f32_16x16x32_bf16 v[60:63], v[130:133], v[172:175], v[60:63]
	v_mfma_f32_16x16x32_bf16 v[64:67], v[106:109], v[180:183], v[64:67]
	v_mfma_f32_16x16x32_bf16 v[68:71], v[130:133], v[180:183], v[68:71]
	v_mfma_f32_16x16x32_bf16 v[72:75], v[106:109], v[188:191], v[72:75]
	v_mfma_f32_16x16x32_bf16 v[76:79], v[130:133], v[188:191], v[76:79]
	v_mfma_f32_16x16x32_bf16 v[48:51], v[110:113], v[142:145], v[48:51]
	v_mfma_f32_16x16x32_bf16 v[52:55], v[134:137], v[142:145], v[52:55]
	v_mfma_f32_16x16x32_bf16 v[56:59], v[110:113], v[176:179], v[56:59]
	v_mfma_f32_16x16x32_bf16 v[60:63], v[134:137], v[176:179], v[60:63]
	v_mfma_f32_16x16x32_bf16 v[64:67], v[110:113], v[184:187], v[64:67]
	v_mfma_f32_16x16x32_bf16 v[68:71], v[134:137], v[184:187], v[68:71]
	v_mfma_f32_16x16x32_bf16 v[72:75], v[110:113], v[192:195], v[72:75]
	v_mfma_f32_16x16x32_bf16 v[76:79], v[134:137], v[192:195], v[76:79]
	s_setprio 0
	s_barrier
	s_mov_b32 m0, s53
	v_lshl_add_u64 v[212:213], v[212:213], 0, s[20:21]
	ds_read_b128 v[196:199], v96
	ds_read_b128 v[200:203], v96 offset:1024
	ds_read_b128 v[204:207], v96 offset:2048
	ds_read_b128 v[208:211], v96 offset:3072
	global_load_lds_dwordx4 v[212:213], off
	v_lshl_add_u64 v[212:213], v[214:215], 0, s[20:21]
	s_mov_b32 m0, s54
	s_nop 0
	global_load_lds_dwordx4 v[212:213], off
	s_barrier
	s_waitcnt lgkmcnt(0)
	s_setprio 1
	s_waitcnt lgkmcnt(0)
	v_mfma_f32_16x16x32_bf16 v[114:117], v[196:199], v[138:141], v[114:117]
	v_mfma_f32_16x16x32_bf16 v[16:19], v[204:207], v[138:141], v[16:19]
	v_mfma_f32_16x16x32_bf16 v[20:23], v[196:199], v[172:175], v[20:23]
	v_mfma_f32_16x16x32_bf16 v[24:27], v[204:207], v[172:175], v[24:27]
	v_mfma_f32_16x16x32_bf16 v[28:31], v[196:199], v[180:183], v[28:31]
	v_mfma_f32_16x16x32_bf16 v[32:35], v[204:207], v[180:183], v[32:35]
	v_mfma_f32_16x16x32_bf16 v[36:39], v[196:199], v[188:191], v[36:39]
	v_mfma_f32_16x16x32_bf16 v[40:43], v[204:207], v[188:191], v[40:43]
	v_mfma_f32_16x16x32_bf16 v[114:117], v[200:203], v[142:145], v[114:117]
	v_mfma_f32_16x16x32_bf16 v[16:19], v[208:211], v[142:145], v[16:19]
	v_mfma_f32_16x16x32_bf16 v[20:23], v[200:203], v[176:179], v[20:23]
	v_mfma_f32_16x16x32_bf16 v[24:27], v[208:211], v[176:179], v[24:27]
	v_mfma_f32_16x16x32_bf16 v[28:31], v[200:203], v[184:187], v[28:31]
	v_mfma_f32_16x16x32_bf16 v[32:35], v[208:211], v[184:187], v[32:35]
	v_mfma_f32_16x16x32_bf16 v[36:39], v[200:203], v[192:195], v[36:39]
	v_mfma_f32_16x16x32_bf16 v[40:43], v[208:211], v[192:195], v[40:43]
	s_setprio 0
	s_mov_b32 m0, s55
	v_lshl_add_u64 v[212:213], v[216:217], 0, s[20:21]
	s_barrier
	ds_read_b128 v[138:141], v91 offset:49152
	ds_read_b128 v[142:145], v91 offset:50176
	ds_read_b128 v[172:175], v91 offset:51200
	ds_read_b128 v[176:179], v91 offset:52224
	ds_read_b128 v[180:183], v91 offset:53248
	ds_read_b128 v[184:187], v91 offset:54272
	ds_read_b128 v[188:191], v91 offset:55296
	ds_read_b128 v[192:195], v91 offset:56320
	global_load_lds_dwordx4 v[212:213], off
	v_lshl_add_u64 v[212:213], v[218:219], 0, s[20:21]
	s_mov_b32 m0, s56
	s_nop 0
	global_load_lds_dwordx4 v[212:213], off
	s_barrier
	s_waitcnt lgkmcnt(0)
	s_setprio 1
	s_waitcnt lgkmcnt(0)
	v_mfma_f32_16x16x32_bf16 v[148:151], v[106:109], v[138:141], v[148:151]
	v_mfma_f32_16x16x32_bf16 v[152:155], v[130:133], v[138:141], v[152:155]
	v_mfma_f32_16x16x32_bf16 v[156:159], v[106:109], v[172:175], v[156:159]
	v_mfma_f32_16x16x32_bf16 v[160:163], v[130:133], v[172:175], v[160:163]
	v_mfma_f32_16x16x32_bf16 v[164:167], v[106:109], v[180:183], v[164:167]
	v_mfma_f32_16x16x32_bf16 v[168:171], v[130:133], v[180:183], v[168:171]
	v_mfma_f32_16x16x32_bf16 v[0:3], v[106:109], v[188:191], v[0:3]
	v_mfma_f32_16x16x32_bf16 v[4:7], v[130:133], v[188:191], v[4:7]
	v_mfma_f32_16x16x32_bf16 v[148:151], v[110:113], v[142:145], v[148:151]
	v_mfma_f32_16x16x32_bf16 v[152:155], v[134:137], v[142:145], v[152:155]
	v_mfma_f32_16x16x32_bf16 v[156:159], v[110:113], v[176:179], v[156:159]
	v_mfma_f32_16x16x32_bf16 v[160:163], v[134:137], v[176:179], v[160:163]
	v_mfma_f32_16x16x32_bf16 v[164:167], v[110:113], v[184:187], v[164:167]
	v_mfma_f32_16x16x32_bf16 v[168:171], v[134:137], v[184:187], v[168:171]
	v_mfma_f32_16x16x32_bf16 v[0:3], v[110:113], v[192:195], v[0:3]
	v_mfma_f32_16x16x32_bf16 v[4:7], v[134:137], v[192:195], v[4:7]
	s_setprio 0
	s_barrier
	s_add_u32 s42, s42, 0x10180
	s_addc_u32 s43, s43, 0
	s_mov_b32 m0, s57
	v_lshl_add_u64 v[106:107], s[42:43], 0, v[84:85]
	global_load_lds_dwordx4 v[106:107], off
	v_lshl_add_u64 v[106:107], s[42:43], 0, v[80:81]
	s_mov_b32 m0, s58
	s_nop 0
	global_load_lds_dwordx4 v[106:107], off
	s_waitcnt vmcnt(6)
	s_barrier
	s_setprio 1
	v_mfma_f32_16x16x32_bf16 v[8:11], v[196:199], v[138:141], v[8:11]
	v_mfma_f32_16x16x32_bf16 v[12:15], v[204:207], v[138:141], v[12:15]
	v_mfma_f32_16x16x32_bf16 v[44:47], v[196:199], v[172:175], v[44:47]
	v_mfma_f32_16x16x32_bf16 v[106:109], v[204:207], v[172:175], v[118:121]
	v_mfma_f32_16x16x32_bf16 v[110:113], v[196:199], v[180:183], v[122:125]
	v_mfma_f32_16x16x32_bf16 v[118:121], v[204:207], v[180:183], v[126:129]
	v_mfma_f32_16x16x32_bf16 v[98:101], v[196:199], v[188:191], v[98:101]
	v_mfma_f32_16x16x32_bf16 v[102:105], v[204:207], v[188:191], v[102:105]
	v_mfma_f32_16x16x32_bf16 v[8:11], v[200:203], v[142:145], v[8:11]
	v_mfma_f32_16x16x32_bf16 v[12:15], v[208:211], v[142:145], v[12:15]
	v_mfma_f32_16x16x32_bf16 v[44:47], v[200:203], v[176:179], v[44:47]
	v_mfma_f32_16x16x32_bf16 v[106:109], v[208:211], v[176:179], v[106:109]
	v_mfma_f32_16x16x32_bf16 v[110:113], v[200:203], v[184:187], v[110:113]
	v_mfma_f32_16x16x32_bf16 v[118:121], v[208:211], v[184:187], v[118:121]
	v_mfma_f32_16x16x32_bf16 v[98:101], v[200:203], v[192:195], v[98:101]
	v_mfma_f32_16x16x32_bf16 v[102:105], v[208:211], v[192:195], v[102:105]
	s_setprio 0
	s_barrier
	ds_read_b128 v[122:125], v93
	ds_read_b128 v[126:129], v93 offset:1024
	ds_read_b128 v[130:133], v93 offset:2048
	ds_read_b128 v[134:137], v93 offset:3072
	s_add_u32 s40, s40, 0x40180
	s_addc_u32 s41, s41, 0
	s_mov_b32 m0, s59
	v_lshl_add_u64 v[196:197], s[40:41], 0, v[86:87]
	ds_read_b128 v[138:141], v91
	ds_read_b128 v[142:145], v91 offset:1024
	ds_read_b128 v[172:175], v91 offset:2048
	ds_read_b128 v[176:179], v91 offset:3072
	ds_read_b128 v[180:183], v91 offset:4096
	ds_read_b128 v[184:187], v91 offset:5120
	ds_read_b128 v[188:191], v91 offset:6144
	ds_read_b128 v[192:195], v91 offset:7168
	global_load_lds_dwordx4 v[196:197], off
	v_lshl_add_u64 v[196:197], s[40:41], 0, v[82:83]
	s_mov_b32 m0, s60
	s_nop 0
	global_load_lds_dwordx4 v[196:197], off
	s_waitcnt lgkmcnt(8)
	s_barrier
	s_waitcnt lgkmcnt(0)
	s_setprio 1
	s_waitcnt lgkmcnt(0)
	v_mfma_f32_16x16x32_bf16 v[48:51], v[122:125], v[138:141], v[48:51]
	v_mfma_f32_16x16x32_bf16 v[52:55], v[130:133], v[138:141], v[52:55]
	v_mfma_f32_16x16x32_bf16 v[56:59], v[122:125], v[172:175], v[56:59]
	v_mfma_f32_16x16x32_bf16 v[60:63], v[130:133], v[172:175], v[60:63]
	v_mfma_f32_16x16x32_bf16 v[64:67], v[122:125], v[180:183], v[64:67]
	v_mfma_f32_16x16x32_bf16 v[68:71], v[130:133], v[180:183], v[68:71]
	v_mfma_f32_16x16x32_bf16 v[72:75], v[122:125], v[188:191], v[72:75]
	v_mfma_f32_16x16x32_bf16 v[76:79], v[130:133], v[188:191], v[76:79]
	v_mfma_f32_16x16x32_bf16 v[48:51], v[126:129], v[142:145], v[48:51]
	v_mfma_f32_16x16x32_bf16 v[52:55], v[134:137], v[142:145], v[52:55]
	v_mfma_f32_16x16x32_bf16 v[56:59], v[126:129], v[176:179], v[56:59]
	v_mfma_f32_16x16x32_bf16 v[60:63], v[134:137], v[176:179], v[60:63]
	v_mfma_f32_16x16x32_bf16 v[64:67], v[126:129], v[184:187], v[64:67]
	v_mfma_f32_16x16x32_bf16 v[68:71], v[134:137], v[184:187], v[68:71]
	v_mfma_f32_16x16x32_bf16 v[72:75], v[126:129], v[192:195], v[72:75]
	v_mfma_f32_16x16x32_bf16 v[76:79], v[134:137], v[192:195], v[76:79]
	s_setprio 0
	s_barrier
	s_mov_b32 m0, s35
	v_lshl_add_u64 v[236:237], s[38:39], 0, v[84:85]
	ds_read_b128 v[196:199], v94
	ds_read_b128 v[200:203], v94 offset:1024
	ds_read_b128 v[204:207], v94 offset:2048
	ds_read_b128 v[208:211], v94 offset:3072
	global_load_lds_dwordx4 v[236:237], off
	v_lshl_add_u64 v[238:239], s[38:39], 0, v[80:81]
	s_mov_b32 m0, s47
	s_nop 0
	global_load_lds_dwordx4 v[238:239], off
	s_barrier
	s_waitcnt lgkmcnt(0)
	s_setprio 1
	s_waitcnt lgkmcnt(0)
	v_mfma_f32_16x16x32_bf16 v[114:117], v[196:199], v[138:141], v[114:117]
	v_mfma_f32_16x16x32_bf16 v[16:19], v[204:207], v[138:141], v[16:19]
	v_mfma_f32_16x16x32_bf16 v[20:23], v[196:199], v[172:175], v[20:23]
	v_mfma_f32_16x16x32_bf16 v[24:27], v[204:207], v[172:175], v[24:27]
	v_mfma_f32_16x16x32_bf16 v[28:31], v[196:199], v[180:183], v[28:31]
	v_mfma_f32_16x16x32_bf16 v[32:35], v[204:207], v[180:183], v[32:35]
	v_mfma_f32_16x16x32_bf16 v[36:39], v[196:199], v[188:191], v[36:39]
	v_mfma_f32_16x16x32_bf16 v[40:43], v[204:207], v[188:191], v[40:43]
	v_mfma_f32_16x16x32_bf16 v[114:117], v[200:203], v[142:145], v[114:117]
	v_mfma_f32_16x16x32_bf16 v[16:19], v[208:211], v[142:145], v[16:19]
	v_mfma_f32_16x16x32_bf16 v[20:23], v[200:203], v[176:179], v[20:23]
	v_mfma_f32_16x16x32_bf16 v[24:27], v[208:211], v[176:179], v[24:27]
	v_mfma_f32_16x16x32_bf16 v[28:31], v[200:203], v[184:187], v[28:31]
	v_mfma_f32_16x16x32_bf16 v[32:35], v[208:211], v[184:187], v[32:35]
	v_mfma_f32_16x16x32_bf16 v[36:39], v[200:203], v[192:195], v[36:39]
	v_mfma_f32_16x16x32_bf16 v[40:43], v[208:211], v[192:195], v[40:43]
	s_setprio 0
	s_mov_b32 m0, s46
	v_lshl_add_u64 v[244:245], s[44:45], 0, v[86:87]
	s_barrier
	ds_read_b128 v[138:141], v91 offset:16384
	ds_read_b128 v[142:145], v91 offset:17408
	ds_read_b128 v[172:175], v91 offset:18432
	ds_read_b128 v[176:179], v91 offset:19456
	ds_read_b128 v[180:183], v91 offset:20480
	ds_read_b128 v[184:187], v91 offset:21504
	ds_read_b128 v[188:191], v91 offset:22528
	ds_read_b128 v[192:195], v91 offset:23552
	global_load_lds_dwordx4 v[244:245], off
	v_lshl_add_u64 v[246:247], s[44:45], 0, v[82:83]
	s_mov_b32 m0, s48
	s_nop 0
	global_load_lds_dwordx4 v[246:247], off
	s_barrier
	s_waitcnt lgkmcnt(0)
	s_setprio 1
	s_waitcnt lgkmcnt(0)
	v_mfma_f32_16x16x32_bf16 v[148:151], v[122:125], v[138:141], v[148:151]
	v_mfma_f32_16x16x32_bf16 v[152:155], v[130:133], v[138:141], v[152:155]
	v_mfma_f32_16x16x32_bf16 v[156:159], v[122:125], v[172:175], v[156:159]
	v_mfma_f32_16x16x32_bf16 v[160:163], v[130:133], v[172:175], v[160:163]
	v_mfma_f32_16x16x32_bf16 v[164:167], v[122:125], v[180:183], v[164:167]
	v_mfma_f32_16x16x32_bf16 v[168:171], v[130:133], v[180:183], v[168:171]
	v_mfma_f32_16x16x32_bf16 v[0:3], v[122:125], v[188:191], v[0:3]
	v_mfma_f32_16x16x32_bf16 v[4:7], v[130:133], v[188:191], v[4:7]
	v_mfma_f32_16x16x32_bf16 v[148:151], v[126:129], v[142:145], v[148:151]
	v_mfma_f32_16x16x32_bf16 v[152:155], v[134:137], v[142:145], v[152:155]
	v_mfma_f32_16x16x32_bf16 v[156:159], v[126:129], v[176:179], v[156:159]
	v_mfma_f32_16x16x32_bf16 v[160:163], v[134:137], v[176:179], v[160:163]
	v_mfma_f32_16x16x32_bf16 v[164:167], v[126:129], v[184:187], v[164:167]
	v_mfma_f32_16x16x32_bf16 v[168:171], v[134:137], v[184:187], v[168:171]
	v_mfma_f32_16x16x32_bf16 v[0:3], v[126:129], v[192:195], v[0:3]
	v_mfma_f32_16x16x32_bf16 v[122:125], v[134:137], v[192:195], v[4:7]
	s_setprio 0
	s_barrier
	s_add_u32 s40, s38, 0x10000
	s_addc_u32 s41, s39, 0
	s_mov_b32 m0, s49
	v_lshl_add_u64 v[4:5], s[40:41], 0, v[84:85]
	global_load_lds_dwordx4 v[4:5], off
	v_lshl_add_u64 v[4:5], s[40:41], 0, v[80:81]
	s_mov_b32 m0, s50
	s_nop 0
	global_load_lds_dwordx4 v[4:5], off
	s_waitcnt vmcnt(6)
	s_barrier
	s_setprio 1
	v_mfma_f32_16x16x32_bf16 v[4:7], v[196:199], v[138:141], v[8:11]
	v_mfma_f32_16x16x32_bf16 v[8:11], v[200:203], v[142:145], v[4:7]
	v_mfma_f32_16x16x32_bf16 v[4:7], v[204:207], v[138:141], v[12:15]
	v_mfma_f32_16x16x32_bf16 v[12:15], v[208:211], v[142:145], v[4:7]
	v_mfma_f32_16x16x32_bf16 v[4:7], v[196:199], v[172:175], v[44:47]
	v_mfma_f32_16x16x32_bf16 v[44:47], v[200:203], v[176:179], v[4:7]
	v_mfma_f32_16x16x32_bf16 v[4:7], v[204:207], v[172:175], v[106:109]
	v_mfma_f32_16x16x32_bf16 v[106:109], v[208:211], v[176:179], v[4:7]
	v_mfma_f32_16x16x32_bf16 v[4:7], v[196:199], v[180:183], v[110:113]
	v_mfma_f32_16x16x32_bf16 v[110:113], v[200:203], v[184:187], v[4:7]
	v_mfma_f32_16x16x32_bf16 v[4:7], v[204:207], v[180:183], v[118:121]
	v_mfma_f32_16x16x32_bf16 v[118:121], v[208:211], v[184:187], v[4:7]
	v_mfma_f32_16x16x32_bf16 v[4:7], v[196:199], v[188:191], v[98:101]
	v_mfma_f32_16x16x32_bf16 v[98:101], v[200:203], v[192:195], v[4:7]
	v_mfma_f32_16x16x32_bf16 v[4:7], v[204:207], v[188:191], v[102:105]
	v_mfma_f32_16x16x32_bf16 v[102:105], v[208:211], v[192:195], v[4:7]
	s_setprio 0
	s_barrier
	s_nop 3
	ds_read_b128 v[4:7], v95
	ds_read_b128 v[126:129], v95 offset:1024
	ds_read_b128 v[130:133], v95 offset:2048
	ds_read_b128 v[134:137], v95 offset:3072
	s_add_u32 s40, s44, 0x40000
	s_addc_u32 s41, s45, 0
	s_mov_b32 m0, s51
	v_lshl_add_u64 v[196:197], s[40:41], 0, v[86:87]
	ds_read_b128 v[138:141], v91 offset:32768
	ds_read_b128 v[142:145], v91 offset:33792
	ds_read_b128 v[172:175], v91 offset:34816
	ds_read_b128 v[176:179], v91 offset:35840
	ds_read_b128 v[180:183], v91 offset:36864
	ds_read_b128 v[184:187], v91 offset:37888
	ds_read_b128 v[188:191], v91 offset:38912
	ds_read_b128 v[192:195], v91 offset:39936
	global_load_lds_dwordx4 v[196:197], off
	v_lshl_add_u64 v[196:197], s[40:41], 0, v[82:83]
	s_mov_b32 m0, s52
	s_nop 0
	global_load_lds_dwordx4 v[196:197], off
	s_waitcnt lgkmcnt(8)
	s_barrier
	s_waitcnt lgkmcnt(0)
	s_setprio 1
	s_waitcnt lgkmcnt(0)
	v_mfma_f32_16x16x32_bf16 v[48:51], v[4:7], v[138:141], v[48:51]
	v_mfma_f32_16x16x32_bf16 v[196:199], v[126:129], v[142:145], v[48:51]
	v_mfma_f32_16x16x32_bf16 v[48:51], v[130:133], v[138:141], v[52:55]
	v_mfma_f32_16x16x32_bf16 v[200:203], v[134:137], v[142:145], v[48:51]
	v_mfma_f32_16x16x32_bf16 v[48:51], v[4:7], v[172:175], v[56:59]
	v_mfma_f32_16x16x32_bf16 v[204:207], v[126:129], v[176:179], v[48:51]
	v_mfma_f32_16x16x32_bf16 v[48:51], v[130:133], v[172:175], v[60:63]
	v_mfma_f32_16x16x32_bf16 v[208:211], v[134:137], v[176:179], v[48:51]
	v_mfma_f32_16x16x32_bf16 v[48:51], v[4:7], v[180:183], v[64:67]
	v_mfma_f32_16x16x32_bf16 v[212:215], v[126:129], v[184:187], v[48:51]
	v_mfma_f32_16x16x32_bf16 v[48:51], v[130:133], v[180:183], v[68:71]
	v_mfma_f32_16x16x32_bf16 v[216:219], v[134:137], v[184:187], v[48:51]
	v_mfma_f32_16x16x32_bf16 v[48:51], v[4:7], v[188:191], v[72:75]
	v_mfma_f32_16x16x32_bf16 v[52:55], v[126:129], v[192:195], v[48:51]
	v_mfma_f32_16x16x32_bf16 v[48:51], v[130:133], v[188:191], v[76:79]
	v_mfma_f32_16x16x32_bf16 v[48:51], v[134:137], v[192:195], v[48:51]
	s_setprio 0
	s_barrier
	s_mov_b32 m0, s53
	v_lshl_add_u64 v[56:57], v[236:237], 0, s[16:17]
	ds_read_b128 v[220:223], v96
	ds_read_b128 v[224:227], v96 offset:1024
	ds_read_b128 v[228:231], v96 offset:2048
	ds_read_b128 v[232:235], v96 offset:3072
	global_load_lds_dwordx4 v[56:57], off
	v_lshl_add_u64 v[56:57], v[238:239], 0, s[16:17]
	s_mov_b32 m0, s54
	s_nop 0
	global_load_lds_dwordx4 v[56:57], off
	s_barrier
	s_waitcnt lgkmcnt(0)
	s_setprio 1
	s_waitcnt lgkmcnt(0)
	v_mfma_f32_16x16x32_bf16 v[16:19], v[228:231], v[138:141], v[16:19]
	v_mfma_f32_16x16x32_bf16 v[56:59], v[220:223], v[138:141], v[114:117]
	v_mfma_f32_16x16x32_bf16 v[138:141], v[232:235], v[142:145], v[16:19]
	v_mfma_f32_16x16x32_bf16 v[16:19], v[220:223], v[172:175], v[20:23]
	v_mfma_f32_16x16x32_bf16 v[114:117], v[224:227], v[142:145], v[56:59]
	v_mfma_f32_16x16x32_bf16 v[142:145], v[224:227], v[176:179], v[16:19]
	v_mfma_f32_16x16x32_bf16 v[16:19], v[228:231], v[172:175], v[24:27]
	v_mfma_f32_16x16x32_bf16 v[172:175], v[232:235], v[176:179], v[16:19]
	v_mfma_f32_16x16x32_bf16 v[16:19], v[220:223], v[180:183], v[28:31]
	v_mfma_f32_16x16x32_bf16 v[176:179], v[224:227], v[184:187], v[16:19]
	v_mfma_f32_16x16x32_bf16 v[16:19], v[228:231], v[180:183], v[32:35]
	v_mfma_f32_16x16x32_bf16 v[180:183], v[232:235], v[184:187], v[16:19]
	v_mfma_f32_16x16x32_bf16 v[16:19], v[220:223], v[188:191], v[36:39]
	v_mfma_f32_16x16x32_bf16 v[68:71], v[224:227], v[192:195], v[16:19]
	v_mfma_f32_16x16x32_bf16 v[16:19], v[228:231], v[188:191], v[40:43]
	v_mfma_f32_16x16x32_bf16 v[60:63], v[232:235], v[192:195], v[16:19]
	s_setprio 0
	s_mov_b32 m0, s55
	s_nop 4
	v_lshl_add_u64 v[16:17], v[244:245], 0, s[16:17]
	s_barrier
	ds_read_b128 v[24:27], v91 offset:49152
	ds_read_b128 v[28:31], v91 offset:50176
	ds_read_b128 v[40:43], v91 offset:51200
	ds_read_b128 v[184:187], v91 offset:52224
	ds_read_b128 v[188:191], v91 offset:53248
	ds_read_b128 v[192:195], v91 offset:54272
	ds_read_b128 v[236:239], v91 offset:55296
	ds_read_b128 v[240:243], v91 offset:56320
	global_load_lds_dwordx4 v[16:17], off
	v_lshl_add_u64 v[16:17], v[246:247], 0, s[16:17]
	s_mov_b32 m0, s56
	s_nop 0
	global_load_lds_dwordx4 v[16:17], off
	s_barrier
	s_waitcnt lgkmcnt(0)
	s_setprio 1
	s_waitcnt lgkmcnt(0)
	v_mfma_f32_16x16x32_bf16 v[16:19], v[4:7], v[24:27], v[148:151]
	v_mfma_f32_16x16x32_bf16 v[64:67], v[126:129], v[28:31], v[16:19]
	v_mfma_f32_16x16x32_bf16 v[16:19], v[130:133], v[24:27], v[152:155]
	v_mfma_f32_16x16x32_bf16 v[56:59], v[134:137], v[28:31], v[16:19]
	v_mfma_f32_16x16x32_bf16 v[16:19], v[4:7], v[40:43], v[156:159]
	v_mfma_f32_16x16x32_bf16 v[36:39], v[126:129], v[184:187], v[16:19]
	v_mfma_f32_16x16x32_bf16 v[16:19], v[130:133], v[40:43], v[160:163]
	v_mfma_f32_16x16x32_bf16 v[32:35], v[134:137], v[184:187], v[16:19]
	v_mfma_f32_16x16x32_bf16 v[16:19], v[4:7], v[188:191], v[164:167]
	v_mfma_f32_16x16x32_bf16 v[0:3], v[4:7], v[236:239], v[0:3]
	v_mfma_f32_16x16x32_bf16 v[20:23], v[126:129], v[192:195], v[16:19]
	v_mfma_f32_16x16x32_bf16 v[16:19], v[130:133], v[188:191], v[168:171]
	v_mfma_f32_16x16x32_bf16 v[4:7], v[126:129], v[240:243], v[0:3]
	v_mfma_f32_16x16x32_bf16 v[0:3], v[130:133], v[236:239], v[122:125]
	v_mfma_f32_16x16x32_bf16 v[16:19], v[134:137], v[192:195], v[16:19]
	v_mfma_f32_16x16x32_bf16 v[0:3], v[134:137], v[240:243], v[0:3]
	s_setprio 0
	s_barrier
	s_add_u32 s38, s38, 0x10080
	s_addc_u32 s39, s39, 0
	s_mov_b32 m0, s57
	v_lshl_add_u64 v[72:73], s[38:39], 0, v[84:85]
	global_load_lds_dwordx4 v[72:73], off
	v_lshl_add_u64 v[72:73], s[38:39], 0, v[80:81]
	s_mov_b32 m0, s58
	s_nop 0
	global_load_lds_dwordx4 v[72:73], off
	s_waitcnt vmcnt(6)
	s_barrier
	s_setprio 1
	v_mfma_f32_16x16x32_bf16 v[8:11], v[220:223], v[24:27], v[8:11]
	v_mfma_f32_16x16x32_bf16 v[76:79], v[224:227], v[28:31], v[8:11]
	v_mfma_f32_16x16x32_bf16 v[8:11], v[228:231], v[24:27], v[12:15]
	v_mfma_f32_16x16x32_bf16 v[72:75], v[232:235], v[28:31], v[8:11]
	v_mfma_f32_16x16x32_bf16 v[8:11], v[220:223], v[40:43], v[44:47]
	v_mfma_f32_16x16x32_bf16 v[44:47], v[224:227], v[184:187], v[8:11]
	v_mfma_f32_16x16x32_bf16 v[8:11], v[228:231], v[40:43], v[106:109]
	v_mfma_f32_16x16x32_bf16 v[40:43], v[232:235], v[184:187], v[8:11]
	v_mfma_f32_16x16x32_bf16 v[8:11], v[220:223], v[188:191], v[110:113]
	v_mfma_f32_16x16x32_bf16 v[28:31], v[224:227], v[192:195], v[8:11]
	v_mfma_f32_16x16x32_bf16 v[8:11], v[228:231], v[188:191], v[118:121]
	v_mfma_f32_16x16x32_bf16 v[24:27], v[232:235], v[192:195], v[8:11]
	v_mfma_f32_16x16x32_bf16 v[8:11], v[220:223], v[236:239], v[98:101]
	v_mfma_f32_16x16x32_bf16 v[12:15], v[224:227], v[240:243], v[8:11]
	v_mfma_f32_16x16x32_bf16 v[8:11], v[228:231], v[236:239], v[102:105]
	v_mfma_f32_16x16x32_bf16 v[8:11], v[232:235], v[240:243], v[8:11]
	s_setprio 0
	s_lshl_b32 s25, s36, 8
	s_and_b32 s25, s25, 0x300
	s_cmp_lt_i32 s36, 4
	s_cselect_b32 s37, s5, s9
	s_cselect_b32 s36, s4, s8
	s_lshl_b32 s27, s34, 18
	v_cvt_pk_bf16_f32 v98, v196, v197
	s_or_b32 s25, s27, s25
	v_cvt_pk_bf16_f32 v99, v198, v199
	v_add_u32_e32 v88, s25, v92
	v_cvt_pk_bf16_f32 v100, v200, v201
	v_cvt_pk_bf16_f32 v101, v202, v203
	v_lshl_add_u64 v[102:103], v[88:89], 1, s[36:37]
	s_barrier
	global_store_dwordx4 v[102:103], v[98:101], off
	s_nop 1
	v_add_u32_e32 v102, 0x80, v88
	v_cvt_pk_bf16_f32 v98, v114, v115
	v_cvt_pk_bf16_f32 v99, v116, v117
	v_cvt_pk_bf16_f32 v100, v138, v139
	v_mov_b32_e32 v103, v89
	v_cvt_pk_bf16_f32 v101, v140, v141
	v_lshl_add_u64 v[102:103], v[102:103], 1, s[36:37]
	global_store_dwordx4 v[102:103], v[98:101], off
	s_nop 1
	v_add_u32_e32 v102, 0x4000, v88
	v_cvt_pk_bf16_f32 v98, v204, v205
	v_cvt_pk_bf16_f32 v99, v206, v207
	v_cvt_pk_bf16_f32 v100, v208, v209
	v_mov_b32_e32 v103, v89
	v_cvt_pk_bf16_f32 v101, v210, v211
	v_lshl_add_u64 v[102:103], v[102:103], 1, s[36:37]
	global_store_dwordx4 v[102:103], v[98:101], off
	s_nop 1
	v_add_u32_e32 v102, 0x4080, v88
	v_cvt_pk_bf16_f32 v98, v142, v143
	v_cvt_pk_bf16_f32 v99, v144, v145
	v_cvt_pk_bf16_f32 v100, v172, v173
	v_mov_b32_e32 v103, v89
	v_cvt_pk_bf16_f32 v101, v174, v175
	v_lshl_add_u64 v[102:103], v[102:103], 1, s[36:37]
	global_store_dwordx4 v[102:103], v[98:101], off
	s_nop 1
	v_add_u32_e32 v102, 0x8000, v88
	v_cvt_pk_bf16_f32 v98, v212, v213
	v_cvt_pk_bf16_f32 v99, v214, v215
	v_cvt_pk_bf16_f32 v100, v216, v217
	v_mov_b32_e32 v103, v89
	v_cvt_pk_bf16_f32 v101, v218, v219
	v_lshl_add_u64 v[102:103], v[102:103], 1, s[36:37]
	global_store_dwordx4 v[102:103], v[98:101], off
	s_nop 1
	v_cvt_pk_bf16_f32 v98, v176, v177
	v_cvt_pk_bf16_f32 v99, v178, v179
	v_cvt_pk_bf16_f32 v52, v52, v53
	v_cvt_pk_bf16_f32 v100, v180, v181
	v_add_u32_e32 v102, 0x8080, v88
	v_mov_b32_e32 v103, v89
	v_cvt_pk_bf16_f32 v101, v182, v183
	v_lshl_add_u64 v[102:103], v[102:103], 1, s[36:37]
	v_cvt_pk_bf16_f32 v53, v54, v55
	v_cvt_pk_bf16_f32 v54, v48, v49
	global_store_dwordx4 v[102:103], v[98:101], off
	s_nop 1
	v_add_u32_e32 v98, 0xc000, v88
	v_mov_b32_e32 v99, v89
	v_cvt_pk_bf16_f32 v55, v50, v51
	v_lshl_add_u64 v[48:49], v[98:99], 1, s[36:37]
	global_store_dwordx4 v[48:49], v[52:55], off
	v_cvt_pk_bf16_f32 v48, v68, v69
	v_cvt_pk_bf16_f32 v49, v70, v71
	v_cvt_pk_bf16_f32 v50, v60, v61
	v_cvt_pk_bf16_f32 v51, v62, v63
	v_add_u32_e32 v52, 0xc080, v88
	v_mov_b32_e32 v53, v89
	v_lshl_add_u64 v[52:53], v[52:53], 1, s[36:37]
	global_store_dwordx4 v[52:53], v[48:51], off
	s_nop 1
	v_cvt_pk_bf16_f32 v48, v64, v65
	v_cvt_pk_bf16_f32 v49, v66, v67
	v_cvt_pk_bf16_f32 v50, v56, v57
	v_add_u32_e32 v52, 0x20000, v88
	v_cvt_pk_bf16_f32 v51, v58, v59
	v_mov_b32_e32 v53, v89
	v_lshl_add_u64 v[52:53], v[52:53], 1, s[36:37]
	global_store_dwordx4 v[52:53], v[48:51], off
	s_nop 1
	v_cvt_pk_bf16_f32 v48, v76, v77
	v_cvt_pk_bf16_f32 v49, v78, v79
	v_cvt_pk_bf16_f32 v50, v72, v73
	v_cvt_pk_bf16_f32 v36, v36, v37
	v_cvt_pk_bf16_f32 v51, v74, v75
	v_add_u32_e32 v52, 0x20080, v88
	v_mov_b32_e32 v53, v89
	v_lshl_add_u64 v[52:53], v[52:53], 1, s[36:37]
	v_cvt_pk_bf16_f32 v37, v38, v39
	v_cvt_pk_bf16_f32 v38, v32, v33
	global_store_dwordx4 v[52:53], v[48:51], off
	s_nop 1
	v_add_u32_e32 v48, 0x24000, v88
	v_mov_b32_e32 v49, v89
	v_cvt_pk_bf16_f32 v39, v34, v35
	v_lshl_add_u64 v[32:33], v[48:49], 1, s[36:37]
	global_store_dwordx4 v[32:33], v[36:39], off
	v_cvt_pk_bf16_f32 v32, v44, v45
	v_cvt_pk_bf16_f32 v33, v46, v47
	v_cvt_pk_bf16_f32 v34, v40, v41
	v_cvt_pk_bf16_f32 v20, v20, v21
	v_cvt_pk_bf16_f32 v35, v42, v43
	v_add_u32_e32 v36, 0x24080, v88
	v_mov_b32_e32 v37, v89
	v_lshl_add_u64 v[36:37], v[36:37], 1, s[36:37]
	v_cvt_pk_bf16_f32 v21, v22, v23
	v_cvt_pk_bf16_f32 v22, v16, v17
	global_store_dwordx4 v[36:37], v[32:35], off
	s_nop 1
	v_add_u32_e32 v32, 0x28000, v88
	v_mov_b32_e32 v33, v89
	v_cvt_pk_bf16_f32 v23, v18, v19
	v_lshl_add_u64 v[16:17], v[32:33], 1, s[36:37]
	global_store_dwordx4 v[16:17], v[20:23], off
	v_cvt_pk_bf16_f32 v16, v28, v29
	v_cvt_pk_bf16_f32 v17, v30, v31
	v_cvt_pk_bf16_f32 v18, v24, v25
	v_cvt_pk_bf16_f32 v4, v4, v5
	v_cvt_pk_bf16_f32 v19, v26, v27
	v_add_u32_e32 v20, 0x28080, v88
	v_mov_b32_e32 v21, v89
	v_lshl_add_u64 v[20:21], v[20:21], 1, s[36:37]
	v_cvt_pk_bf16_f32 v5, v6, v7
	v_cvt_pk_bf16_f32 v6, v0, v1
	global_store_dwordx4 v[20:21], v[16:19], off
	s_nop 1
	v_add_u32_e32 v16, 0x2c000, v88
	v_mov_b32_e32 v17, v89
	v_cvt_pk_bf16_f32 v7, v2, v3
	v_lshl_add_u64 v[0:1], v[16:17], 1, s[36:37]
	global_store_dwordx4 v[0:1], v[4:7], off
	v_cvt_pk_bf16_f32 v0, v12, v13
	v_cvt_pk_bf16_f32 v1, v14, v15
	v_cvt_pk_bf16_f32 v2, v8, v9
	v_add_u32_e32 v88, 0x2c080, v88
	v_cvt_pk_bf16_f32 v3, v10, v11
	v_lshl_add_u64 v[4:5], v[88:89], 1, s[36:37]
	s_andn2_b64 vcc, exec, s[22:23]
	s_mov_b32 s36, s24
	s_mov_b32 s34, s26
	s_mov_b64 s[42:43], s[30:31]
	s_mov_b64 s[40:41], s[28:29]
	global_store_dwordx4 v[4:5], v[0:3], off
	s_cbranch_vccz .LBB0_457

.LBB0_471:
	s_add_u32 s41, s34, s40
	s_addc_u32 s49, s35, 0
	s_add_u32 s44, s41, 0x100
	s_addc_u32 s45, s49, 0
	s_and_b64 s[42:43], s[38:39], exec
	s_cselect_b32 s45, s5, s45
	s_cselect_b32 s44, s29, s44
	s_add_u32 s40, s30, s40
	s_addc_u32 s42, s31, 0
	s_add_u32 s40, s40, 0x100
	s_addc_u32 s42, s42, 0
	s_and_b64 s[38:39], s[38:39], exec
	s_cselect_b32 s47, s21, s42
	s_cselect_b32 s46, s23, s40
	s_add_u32 s48, s41, 0x10080
	ds_read_b128 v[148:151], v141
	ds_read_b128 v[152:155], v141 offset:1024
	ds_read_b128 v[156:159], v141 offset:2048
	ds_read_b128 v[160:163], v141 offset:3072
	s_addc_u32 s49, s49, 0
	s_add_u32 s40, s46, 0x40000
	s_addc_u32 s41, s47, 0
	s_add_u32 s38, s44, 0x10000
	s_addc_u32 s39, s45, 0
	s_add_u32 s42, s46, 0x40080
	s_addc_u32 s43, s47, 0
	s_mov_b32 m0, s64
	v_lshl_add_u64 v[196:197], s[48:49], 0, v[128:129]
	ds_read_b128 v[164:167], v139
	ds_read_b128 v[168:171], v139 offset:1024
	ds_read_b128 v[172:175], v139 offset:2048
	ds_read_b128 v[176:179], v139 offset:3072
	ds_read_b128 v[180:183], v139 offset:4096
	ds_read_b128 v[184:187], v139 offset:5120
	ds_read_b128 v[188:191], v139 offset:6144
	ds_read_b128 v[192:195], v139 offset:7168
	global_load_lds_dwordx4 v[196:197], off
	v_lshl_add_u64 v[196:197], s[48:49], 0, v[132:133]
	s_mov_b32 m0, s65
	s_nop 0
	global_load_lds_dwordx4 v[196:197], off
	s_waitcnt lgkmcnt(8)
	s_barrier
	s_waitcnt lgkmcnt(0)
	s_setprio 1
	s_waitcnt lgkmcnt(0)
	v_mfma_f32_16x16x32_bf16 v[124:127], v[148:151], v[164:167], v[124:127]
	v_mfma_f32_16x16x32_bf16 v[120:123], v[156:159], v[164:167], v[120:123]
	v_mfma_f32_16x16x32_bf16 v[108:111], v[148:151], v[172:175], v[108:111]
	v_mfma_f32_16x16x32_bf16 v[104:107], v[156:159], v[172:175], v[104:107]
	v_mfma_f32_16x16x32_bf16 v[92:95], v[148:151], v[180:183], v[92:95]
	v_mfma_f32_16x16x32_bf16 v[88:91], v[156:159], v[180:183], v[88:91]
	v_mfma_f32_16x16x32_bf16 v[76:79], v[148:151], v[188:191], v[76:79]
	v_mfma_f32_16x16x32_bf16 v[72:75], v[156:159], v[188:191], v[72:75]
	v_mfma_f32_16x16x32_bf16 v[124:127], v[152:155], v[168:171], v[124:127]
	v_mfma_f32_16x16x32_bf16 v[120:123], v[160:163], v[168:171], v[120:123]
	v_mfma_f32_16x16x32_bf16 v[108:111], v[152:155], v[176:179], v[108:111]
	v_mfma_f32_16x16x32_bf16 v[104:107], v[160:163], v[176:179], v[104:107]
	v_mfma_f32_16x16x32_bf16 v[92:95], v[152:155], v[184:187], v[92:95]
	v_mfma_f32_16x16x32_bf16 v[88:91], v[160:163], v[184:187], v[88:91]
	v_mfma_f32_16x16x32_bf16 v[76:79], v[152:155], v[192:195], v[76:79]
	v_mfma_f32_16x16x32_bf16 v[72:75], v[160:163], v[192:195], v[72:75]
	s_setprio 0
	s_barrier
	s_mov_b32 m0, s50
	v_lshl_add_u64 v[212:213], s[46:47], 0, v[130:131]
	ds_read_b128 v[196:199], v142
	ds_read_b128 v[200:203], v142 offset:1024
	ds_read_b128 v[204:207], v142 offset:2048
	ds_read_b128 v[208:211], v142 offset:3072
	global_load_lds_dwordx4 v[212:213], off
	v_lshl_add_u64 v[214:215], s[46:47], 0, v[134:135]
	s_mov_b32 m0, s51
	s_nop 0
	global_load_lds_dwordx4 v[214:215], off
	s_barrier
	s_waitcnt lgkmcnt(0)
	s_setprio 1
	s_waitcnt lgkmcnt(0)
	v_mfma_f32_16x16x32_bf16 v[116:119], v[196:199], v[164:167], v[116:119]
	v_mfma_f32_16x16x32_bf16 v[112:115], v[204:207], v[164:167], v[112:115]
	v_mfma_f32_16x16x32_bf16 v[100:103], v[196:199], v[172:175], v[100:103]
	v_mfma_f32_16x16x32_bf16 v[96:99], v[204:207], v[172:175], v[96:99]
	v_mfma_f32_16x16x32_bf16 v[84:87], v[196:199], v[180:183], v[84:87]
	v_mfma_f32_16x16x32_bf16 v[80:83], v[204:207], v[180:183], v[80:83]
	v_mfma_f32_16x16x32_bf16 v[68:71], v[196:199], v[188:191], v[68:71]
	v_mfma_f32_16x16x32_bf16 v[64:67], v[204:207], v[188:191], v[64:67]
	v_mfma_f32_16x16x32_bf16 v[116:119], v[200:203], v[168:171], v[116:119]
	v_mfma_f32_16x16x32_bf16 v[112:115], v[208:211], v[168:171], v[112:115]
	v_mfma_f32_16x16x32_bf16 v[100:103], v[200:203], v[176:179], v[100:103]
	v_mfma_f32_16x16x32_bf16 v[96:99], v[208:211], v[176:179], v[96:99]
	v_mfma_f32_16x16x32_bf16 v[84:87], v[200:203], v[184:187], v[84:87]
	v_mfma_f32_16x16x32_bf16 v[80:83], v[208:211], v[184:187], v[80:83]
	v_mfma_f32_16x16x32_bf16 v[68:71], v[200:203], v[192:195], v[68:71]
	v_mfma_f32_16x16x32_bf16 v[64:67], v[208:211], v[192:195], v[64:67]
	s_setprio 0
	s_mov_b32 m0, s3
	v_lshl_add_u64 v[216:217], s[44:45], 0, v[128:129]
	s_barrier
	ds_read_b128 v[164:167], v139 offset:16384
	ds_read_b128 v[168:171], v139 offset:17408
	ds_read_b128 v[172:175], v139 offset:18432
	ds_read_b128 v[176:179], v139 offset:19456
	ds_read_b128 v[180:183], v139 offset:20480
	ds_read_b128 v[184:187], v139 offset:21504
	ds_read_b128 v[188:191], v139 offset:22528
	ds_read_b128 v[192:195], v139 offset:23552
	global_load_lds_dwordx4 v[216:217], off
	v_lshl_add_u64 v[218:219], s[44:45], 0, v[132:133]
	s_mov_b32 m0, s52
	s_nop 0
	global_load_lds_dwordx4 v[218:219], off
	s_barrier
	s_waitcnt lgkmcnt(0)
	s_setprio 1
	s_waitcnt lgkmcnt(0)
	v_mfma_f32_16x16x32_bf16 v[60:63], v[148:151], v[164:167], v[60:63]
	v_mfma_f32_16x16x32_bf16 v[56:59], v[156:159], v[164:167], v[56:59]
	v_mfma_f32_16x16x32_bf16 v[44:47], v[148:151], v[172:175], v[44:47]
	v_mfma_f32_16x16x32_bf16 v[40:43], v[156:159], v[172:175], v[40:43]
	v_mfma_f32_16x16x32_bf16 v[28:31], v[148:151], v[180:183], v[28:31]
	v_mfma_f32_16x16x32_bf16 v[24:27], v[156:159], v[180:183], v[24:27]
	v_mfma_f32_16x16x32_bf16 v[12:15], v[148:151], v[188:191], v[12:15]
	v_mfma_f32_16x16x32_bf16 v[8:11], v[156:159], v[188:191], v[8:11]
	v_mfma_f32_16x16x32_bf16 v[60:63], v[152:155], v[168:171], v[60:63]
	v_mfma_f32_16x16x32_bf16 v[56:59], v[160:163], v[168:171], v[56:59]
	v_mfma_f32_16x16x32_bf16 v[44:47], v[152:155], v[176:179], v[44:47]
	v_mfma_f32_16x16x32_bf16 v[40:43], v[160:163], v[176:179], v[40:43]
	v_mfma_f32_16x16x32_bf16 v[28:31], v[152:155], v[184:187], v[28:31]
	v_mfma_f32_16x16x32_bf16 v[24:27], v[160:163], v[184:187], v[24:27]
	v_mfma_f32_16x16x32_bf16 v[12:15], v[152:155], v[192:195], v[12:15]
	v_mfma_f32_16x16x32_bf16 v[8:11], v[160:163], v[192:195], v[8:11]
	s_setprio 0
	s_barrier
	s_mov_b32 m0, s53
	v_lshl_add_u64 v[148:149], s[40:41], 0, v[130:131]
	global_load_lds_dwordx4 v[148:149], off
	v_lshl_add_u64 v[148:149], s[40:41], 0, v[134:135]
	s_mov_b32 m0, s54
	s_nop 0
	global_load_lds_dwordx4 v[148:149], off
	s_waitcnt vmcnt(6)
	s_barrier
	s_setprio 1
	v_mfma_f32_16x16x32_bf16 v[52:55], v[196:199], v[164:167], v[52:55]
	v_mfma_f32_16x16x32_bf16 v[48:51], v[204:207], v[164:167], v[48:51]
	v_mfma_f32_16x16x32_bf16 v[36:39], v[196:199], v[172:175], v[36:39]
	v_mfma_f32_16x16x32_bf16 v[32:35], v[204:207], v[172:175], v[32:35]
	v_mfma_f32_16x16x32_bf16 v[20:23], v[196:199], v[180:183], v[20:23]
	v_mfma_f32_16x16x32_bf16 v[16:19], v[204:207], v[180:183], v[16:19]
	v_mfma_f32_16x16x32_bf16 v[4:7], v[196:199], v[188:191], v[4:7]
	v_mfma_f32_16x16x32_bf16 v[0:3], v[204:207], v[188:191], v[0:3]
	v_mfma_f32_16x16x32_bf16 v[52:55], v[200:203], v[168:171], v[52:55]
	v_mfma_f32_16x16x32_bf16 v[48:51], v[208:211], v[168:171], v[48:51]
	v_mfma_f32_16x16x32_bf16 v[36:39], v[200:203], v[176:179], v[36:39]
	v_mfma_f32_16x16x32_bf16 v[32:35], v[208:211], v[176:179], v[32:35]
	v_mfma_f32_16x16x32_bf16 v[20:23], v[200:203], v[184:187], v[20:23]
	v_mfma_f32_16x16x32_bf16 v[16:19], v[208:211], v[184:187], v[16:19]
	v_mfma_f32_16x16x32_bf16 v[4:7], v[200:203], v[192:195], v[4:7]
	v_mfma_f32_16x16x32_bf16 v[0:3], v[208:211], v[192:195], v[0:3]
	s_setprio 0
	s_barrier
	ds_read_b128 v[148:151], v143
	ds_read_b128 v[152:155], v143 offset:1024
	ds_read_b128 v[156:159], v143 offset:2048
	ds_read_b128 v[160:163], v143 offset:3072
	s_mov_b32 m0, s55
	v_lshl_add_u64 v[196:197], s[38:39], 0, v[128:129]
	ds_read_b128 v[164:167], v139 offset:32768
	ds_read_b128 v[168:171], v139 offset:33792
	ds_read_b128 v[172:175], v139 offset:34816
	ds_read_b128 v[176:179], v139 offset:35840
	ds_read_b128 v[180:183], v139 offset:36864
	ds_read_b128 v[184:187], v139 offset:37888
	ds_read_b128 v[188:191], v139 offset:38912
	ds_read_b128 v[192:195], v139 offset:39936
	global_load_lds_dwordx4 v[196:197], off
	v_lshl_add_u64 v[196:197], s[38:39], 0, v[132:133]
	s_mov_b32 m0, s56
	s_nop 0
	global_load_lds_dwordx4 v[196:197], off
	s_waitcnt lgkmcnt(8)
	s_barrier
	s_waitcnt lgkmcnt(0)
	s_setprio 1
	s_waitcnt lgkmcnt(0)
	v_mfma_f32_16x16x32_bf16 v[124:127], v[148:151], v[164:167], v[124:127]
	v_mfma_f32_16x16x32_bf16 v[120:123], v[156:159], v[164:167], v[120:123]
	v_mfma_f32_16x16x32_bf16 v[108:111], v[148:151], v[172:175], v[108:111]
	v_mfma_f32_16x16x32_bf16 v[104:107], v[156:159], v[172:175], v[104:107]
	v_mfma_f32_16x16x32_bf16 v[92:95], v[148:151], v[180:183], v[92:95]
	v_mfma_f32_16x16x32_bf16 v[88:91], v[156:159], v[180:183], v[88:91]
	v_mfma_f32_16x16x32_bf16 v[76:79], v[148:151], v[188:191], v[76:79]
	v_mfma_f32_16x16x32_bf16 v[72:75], v[156:159], v[188:191], v[72:75]
	v_mfma_f32_16x16x32_bf16 v[124:127], v[152:155], v[168:171], v[124:127]
	v_mfma_f32_16x16x32_bf16 v[120:123], v[160:163], v[168:171], v[120:123]
	v_mfma_f32_16x16x32_bf16 v[108:111], v[152:155], v[176:179], v[108:111]
	v_mfma_f32_16x16x32_bf16 v[104:107], v[160:163], v[176:179], v[104:107]
	v_mfma_f32_16x16x32_bf16 v[92:95], v[152:155], v[184:187], v[92:95]
	v_mfma_f32_16x16x32_bf16 v[88:91], v[160:163], v[184:187], v[88:91]
	v_mfma_f32_16x16x32_bf16 v[76:79], v[152:155], v[192:195], v[76:79]
	v_mfma_f32_16x16x32_bf16 v[72:75], v[160:163], v[192:195], v[72:75]
	s_setprio 0
	s_barrier
	s_mov_b32 m0, s57
	v_lshl_add_u64 v[212:213], v[212:213], 0, s[8:9]
	ds_read_b128 v[196:199], v144
	ds_read_b128 v[200:203], v144 offset:1024
	ds_read_b128 v[204:207], v144 offset:2048
	ds_read_b128 v[208:211], v144 offset:3072
	global_load_lds_dwordx4 v[212:213], off
	v_lshl_add_u64 v[212:213], v[214:215], 0, s[8:9]
	s_mov_b32 m0, s58
	s_nop 0
	global_load_lds_dwordx4 v[212:213], off
	s_barrier
	s_waitcnt lgkmcnt(0)
	s_setprio 1
	s_waitcnt lgkmcnt(0)
	v_mfma_f32_16x16x32_bf16 v[116:119], v[196:199], v[164:167], v[116:119]
	v_mfma_f32_16x16x32_bf16 v[112:115], v[204:207], v[164:167], v[112:115]
	v_mfma_f32_16x16x32_bf16 v[100:103], v[196:199], v[172:175], v[100:103]
	v_mfma_f32_16x16x32_bf16 v[96:99], v[204:207], v[172:175], v[96:99]
	v_mfma_f32_16x16x32_bf16 v[84:87], v[196:199], v[180:183], v[84:87]
	v_mfma_f32_16x16x32_bf16 v[80:83], v[204:207], v[180:183], v[80:83]
	v_mfma_f32_16x16x32_bf16 v[68:71], v[196:199], v[188:191], v[68:71]
	v_mfma_f32_16x16x32_bf16 v[64:67], v[204:207], v[188:191], v[64:67]
	v_mfma_f32_16x16x32_bf16 v[116:119], v[200:203], v[168:171], v[116:119]
	v_mfma_f32_16x16x32_bf16 v[112:115], v[208:211], v[168:171], v[112:115]
	v_mfma_f32_16x16x32_bf16 v[100:103], v[200:203], v[176:179], v[100:103]
	v_mfma_f32_16x16x32_bf16 v[96:99], v[208:211], v[176:179], v[96:99]
	v_mfma_f32_16x16x32_bf16 v[84:87], v[200:203], v[184:187], v[84:87]
	v_mfma_f32_16x16x32_bf16 v[80:83], v[208:211], v[184:187], v[80:83]
	v_mfma_f32_16x16x32_bf16 v[68:71], v[200:203], v[192:195], v[68:71]
	v_mfma_f32_16x16x32_bf16 v[64:67], v[208:211], v[192:195], v[64:67]
	s_setprio 0
	s_mov_b32 m0, s59
	v_lshl_add_u64 v[212:213], v[216:217], 0, s[8:9]
	s_barrier
	ds_read_b128 v[164:167], v139 offset:49152
	ds_read_b128 v[168:171], v139 offset:50176
	ds_read_b128 v[172:175], v139 offset:51200
	ds_read_b128 v[176:179], v139 offset:52224
	ds_read_b128 v[180:183], v139 offset:53248
	ds_read_b128 v[184:187], v139 offset:54272
	ds_read_b128 v[188:191], v139 offset:55296
	ds_read_b128 v[192:195], v139 offset:56320
	global_load_lds_dwordx4 v[212:213], off
	v_lshl_add_u64 v[212:213], v[218:219], 0, s[8:9]
	s_mov_b32 m0, s60
	s_nop 0
	global_load_lds_dwordx4 v[212:213], off
	s_barrier
	s_waitcnt lgkmcnt(0)
	s_setprio 1
	s_waitcnt lgkmcnt(0)
	v_mfma_f32_16x16x32_bf16 v[60:63], v[148:151], v[164:167], v[60:63]
	v_mfma_f32_16x16x32_bf16 v[56:59], v[156:159], v[164:167], v[56:59]
	v_mfma_f32_16x16x32_bf16 v[44:47], v[148:151], v[172:175], v[44:47]
	v_mfma_f32_16x16x32_bf16 v[40:43], v[156:159], v[172:175], v[40:43]
	v_mfma_f32_16x16x32_bf16 v[28:31], v[148:151], v[180:183], v[28:31]
	v_mfma_f32_16x16x32_bf16 v[24:27], v[156:159], v[180:183], v[24:27]
	v_mfma_f32_16x16x32_bf16 v[12:15], v[148:151], v[188:191], v[12:15]
	v_mfma_f32_16x16x32_bf16 v[8:11], v[156:159], v[188:191], v[8:11]
	v_mfma_f32_16x16x32_bf16 v[60:63], v[152:155], v[168:171], v[60:63]
	v_mfma_f32_16x16x32_bf16 v[56:59], v[160:163], v[168:171], v[56:59]
	v_mfma_f32_16x16x32_bf16 v[44:47], v[152:155], v[176:179], v[44:47]
	v_mfma_f32_16x16x32_bf16 v[40:43], v[160:163], v[176:179], v[40:43]
	v_mfma_f32_16x16x32_bf16 v[28:31], v[152:155], v[184:187], v[28:31]
	v_mfma_f32_16x16x32_bf16 v[24:27], v[160:163], v[184:187], v[24:27]
	v_mfma_f32_16x16x32_bf16 v[12:15], v[152:155], v[192:195], v[12:15]
	v_mfma_f32_16x16x32_bf16 v[8:11], v[160:163], v[192:195], v[8:11]
	s_setprio 0
	s_barrier
	s_mov_b32 m0, s61
	v_lshl_add_u64 v[148:149], s[42:43], 0, v[130:131]
	global_load_lds_dwordx4 v[148:149], off
	v_lshl_add_u64 v[148:149], s[42:43], 0, v[134:135]
	s_mov_b32 m0, s62
	s_nop 0
	global_load_lds_dwordx4 v[148:149], off
	s_waitcnt vmcnt(6)
	s_barrier
	s_setprio 1
	v_mfma_f32_16x16x32_bf16 v[52:55], v[196:199], v[164:167], v[52:55]
	v_mfma_f32_16x16x32_bf16 v[48:51], v[204:207], v[164:167], v[48:51]
	v_mfma_f32_16x16x32_bf16 v[36:39], v[196:199], v[172:175], v[36:39]
	v_mfma_f32_16x16x32_bf16 v[32:35], v[204:207], v[172:175], v[32:35]
	v_mfma_f32_16x16x32_bf16 v[20:23], v[196:199], v[180:183], v[20:23]
	v_mfma_f32_16x16x32_bf16 v[16:19], v[204:207], v[180:183], v[16:19]
	v_mfma_f32_16x16x32_bf16 v[4:7], v[196:199], v[188:191], v[4:7]
	v_mfma_f32_16x16x32_bf16 v[0:3], v[204:207], v[188:191], v[0:3]
	v_mfma_f32_16x16x32_bf16 v[52:55], v[200:203], v[168:171], v[52:55]
	v_mfma_f32_16x16x32_bf16 v[48:51], v[208:211], v[168:171], v[48:51]
	v_mfma_f32_16x16x32_bf16 v[36:39], v[200:203], v[176:179], v[36:39]
	v_mfma_f32_16x16x32_bf16 v[32:35], v[208:211], v[176:179], v[32:35]
	v_mfma_f32_16x16x32_bf16 v[20:23], v[200:203], v[184:187], v[20:23]
	v_mfma_f32_16x16x32_bf16 v[16:19], v[208:211], v[184:187], v[16:19]
	v_mfma_f32_16x16x32_bf16 v[4:7], v[200:203], v[192:195], v[4:7]
	v_mfma_f32_16x16x32_bf16 v[0:3], v[208:211], v[192:195], v[0:3]
	s_setprio 0
	s_movk_i32 s40, 0x100
	s_andn2_b64 vcc, exec, s[36:37]
	s_mov_b64 s[38:39], -1
	s_mov_b64 s[36:37], 0
	s_barrier
	s_cbranch_vccz .LBB0_471
	s_cmp_gt_i32 s28, 3
	s_mov_b64 s[30:31], -1
	s_cbranch_scc0 .LBB0_474
	s_and_saveexec_b64 s[30:31], s[16:17]
	s_or_b64 exec, exec, s[30:31]
	s_mov_b64 s[30:31], 0

.LBB0_969:
	s_or_b64 exec, exec, s[20:21]
	v_add_u32_e32 v24, 0x18000, v13
	v_lshl_add_u64 v[8:9], s[18:19], 0, v[0:1]
	v_mov_b32_e32 v3, v1
	v_readfirstlane_b32 s35, v24
	v_add_u32_e32 v24, 0x1a000, v13
	v_lshl_add_u64 v[10:11], s[18:19], 0, v[2:3]
	v_lshl_add_u64 v[22:23], v[8:9], 0, s[84:85]
	s_mov_b32 m0, s35
	v_readfirstlane_b32 s34, v24
	v_add_u32_e32 v24, 0x8000, v13
	v_lshl_add_u64 v[6:7], s[6:7], 0, v[0:1]
	s_waitcnt vmcnt(4)
	s_barrier
	global_load_lds_dwordx4 v[22:23], off
	v_lshl_add_u64 v[22:23], v[10:11], 0, s[84:85]
	s_mov_b32 m0, s34
	v_readfirstlane_b32 s30, v24
	v_add_u32_e32 v24, 0xa000, v13
	v_lshl_add_u64 v[4:5], s[6:7], 0, v[2:3]
	global_load_lds_dwordx4 v[22:23], off
	v_lshl_add_u64 v[22:23], v[6:7], 0, s[84:85]
	s_mov_b32 m0, s30
	v_readfirstlane_b32 s29, v24
	s_add_u32 s20, s18, 0x10080
	v_add_u32_e32 v24, 0x1c000, v13
	global_load_lds_dwordx4 v[22:23], off
	v_lshl_add_u64 v[22:23], v[4:5], 0, s[84:85]
	s_mov_b32 m0, s29
	s_addc_u32 s21, s19, 0
	v_readfirstlane_b32 s15, v24
	v_add_u32_e32 v24, 0x1e000, v13
	global_load_lds_dwordx4 v[22:23], off
	v_lshl_add_u64 v[22:23], s[20:21], 0, v[0:1]
	s_mov_b32 m0, s15
	v_readfirstlane_b32 s2, v24
	global_load_lds_dwordx4 v[22:23], off
	v_lshl_add_u64 v[22:23], s[20:21], 0, v[2:3]
	s_mov_b32 m0, s2
	s_add_u32 s36, s6, 0x10080
	global_load_lds_dwordx4 v[22:23], off
	v_and_b32_e32 v22, 15, v12
	v_and_b32_e32 v23, 48, v12
	v_lshlrev_b32_e32 v12, 2, v12
	v_lshlrev_b32_e32 v22, 6, v22
	v_and_b32_e32 v12, 32, v12
	v_or_b32_e32 v24, v22, v23
	v_bitop3_b32 v22, v22, v12, v23 bitop3:0x36
	v_lshlrev_b32_e32 v23, 6, v130
	v_and_or_b32 v131, v23, s38, v22
	v_lshlrev_b32_e32 v21, 13, v21
	s_addc_u32 s37, s7, 0
	v_or_b32_e32 v133, 0x10000, v131
	v_or_b32_e32 v179, 0x10800, v131
	v_bitop3_b32 v12, v24, v21, v12 bitop3:0xde
	s_waitcnt vmcnt(6)
	s_barrier
	s_add_u32 s22, s18, 0x10100
	v_or_b32_e32 v178, 0x10400, v131
	ds_read_b128 v[22:25], v133
	ds_read_b128 v[26:29], v178
	v_or_b32_e32 v214, 0x10c00, v131
	ds_read_b128 v[30:33], v179
	ds_read_b128 v[34:37], v214
	s_addc_u32 s23, s19, 0
	s_add_u32 s20, s6, 0x10100
	s_addc_u32 s21, s7, 0
	s_add_u32 s18, s18, 0x10180
	s_addc_u32 s19, s19, 0
	v_add_u32_e32 v21, 0xc000, v13
	v_lshl_add_u64 v[70:71], s[36:37], 0, v[0:1]
	v_readfirstlane_b32 s31, v21
	v_add_u32_e32 v21, 0xe000, v13
	s_mov_b32 m0, s31
	v_readfirstlane_b32 s17, v21
	ds_read_b128 v[38:41], v12
	ds_read_b128 v[42:45], v12 offset:1024
	ds_read_b128 v[46:49], v12 offset:2048
	ds_read_b128 v[50:53], v12 offset:3072
	ds_read_b128 v[54:57], v12 offset:4096
	ds_read_b128 v[58:61], v12 offset:5120
	ds_read_b128 v[62:65], v12 offset:6144
	ds_read_b128 v[66:69], v12 offset:7168
	global_load_lds_dwordx4 v[70:71], off
	v_lshl_add_u64 v[70:71], s[36:37], 0, v[2:3]
	s_mov_b32 m0, s17
	s_nop 0
	global_load_lds_dwordx4 v[70:71], off
	s_waitcnt lgkmcnt(8)
	s_barrier
	s_waitcnt lgkmcnt(0)
	s_setprio 1
	s_waitcnt lgkmcnt(0)
	v_mfma_f32_16x16x32_bf16 v[70:73], v[38:41], v[22:25], 0
	v_mfma_f32_16x16x32_bf16 v[74:77], v[38:41], v[30:33], 0
	v_mfma_f32_16x16x32_bf16 v[78:81], v[46:49], v[22:25], 0
	v_mfma_f32_16x16x32_bf16 v[82:85], v[46:49], v[30:33], 0
	v_mfma_f32_16x16x32_bf16 v[86:89], v[54:57], v[22:25], 0
	v_mfma_f32_16x16x32_bf16 v[90:93], v[54:57], v[30:33], 0
	v_mfma_f32_16x16x32_bf16 v[94:97], v[62:65], v[22:25], 0
	v_mfma_f32_16x16x32_bf16 v[98:101], v[62:65], v[30:33], 0
	v_mfma_f32_16x16x32_bf16 v[70:73], v[42:45], v[26:29], v[70:73]
	v_mfma_f32_16x16x32_bf16 v[74:77], v[42:45], v[34:37], v[74:77]
	v_mfma_f32_16x16x32_bf16 v[78:81], v[50:53], v[26:29], v[78:81]
	v_mfma_f32_16x16x32_bf16 v[82:85], v[50:53], v[34:37], v[82:85]
	v_mfma_f32_16x16x32_bf16 v[86:89], v[58:61], v[26:29], v[86:89]
	v_mfma_f32_16x16x32_bf16 v[90:93], v[58:61], v[34:37], v[90:93]
	v_mfma_f32_16x16x32_bf16 v[94:97], v[66:69], v[26:29], v[94:97]
	v_mfma_f32_16x16x32_bf16 v[98:101], v[66:69], v[34:37], v[98:101]
	s_setprio 0
	s_barrier
	v_readfirstlane_b32 s36, v19
	v_or_b32_e32 v215, 0x14000, v131
	v_or_b32_e32 v217, 0x14800, v131
	v_lshl_add_u64 v[118:119], v[8:9], 0, s[86:87]
	s_mov_b32 m0, s36
	v_readfirstlane_b32 s36, v20
	v_or_b32_e32 v216, 0x14400, v131
	ds_read_b128 v[102:105], v215
	ds_read_b128 v[106:109], v216
	v_or_b32_e32 v221, 0x14c00, v131
	ds_read_b128 v[110:113], v217
	ds_read_b128 v[114:117], v221
	global_load_lds_dwordx4 v[118:119], off
	v_lshl_add_u64 v[118:119], v[10:11], 0, s[86:87]
	s_mov_b32 m0, s36
	s_nop 0
	global_load_lds_dwordx4 v[118:119], off
	s_barrier
	s_waitcnt lgkmcnt(0)
	s_setprio 1
	s_waitcnt lgkmcnt(0)
	v_mfma_f32_16x16x32_bf16 v[118:121], v[38:41], v[102:105], 0
	v_mfma_f32_16x16x32_bf16 v[38:41], v[38:41], v[110:113], 0
	v_mfma_f32_16x16x32_bf16 v[118:121], v[42:45], v[106:109], v[118:121]
	v_mfma_f32_16x16x32_bf16 v[38:41], v[42:45], v[114:117], v[38:41]
	v_mfma_f32_16x16x32_bf16 v[42:45], v[46:49], v[102:105], 0
	v_mfma_f32_16x16x32_bf16 v[46:49], v[46:49], v[110:113], 0
	v_mfma_f32_16x16x32_bf16 v[42:45], v[50:53], v[106:109], v[42:45]
	v_mfma_f32_16x16x32_bf16 v[46:49], v[50:53], v[114:117], v[46:49]
	v_mfma_f32_16x16x32_bf16 v[50:53], v[54:57], v[102:105], 0
	v_mfma_f32_16x16x32_bf16 v[54:57], v[54:57], v[110:113], 0
	v_mfma_f32_16x16x32_bf16 v[50:53], v[58:61], v[106:109], v[50:53]
	v_mfma_f32_16x16x32_bf16 v[54:57], v[58:61], v[114:117], v[54:57]
	v_mfma_f32_16x16x32_bf16 v[58:61], v[62:65], v[102:105], 0
	v_mfma_f32_16x16x32_bf16 v[62:65], v[62:65], v[110:113], 0
	v_mfma_f32_16x16x32_bf16 v[58:61], v[66:69], v[106:109], v[58:61]
	v_mfma_f32_16x16x32_bf16 v[62:65], v[66:69], v[114:117], v[62:65]
	s_setprio 0
	v_readfirstlane_b32 s36, v13
	v_lshl_add_u64 v[20:21], v[6:7], 0, s[86:87]
	s_mov_b32 m0, s36
	v_readfirstlane_b32 s36, v16
	s_barrier
	ds_read_b128 v[66:69], v12 offset:16384
	ds_read_b128 v[122:125], v12 offset:17408
	ds_read_b128 v[126:129], v12 offset:18432
	ds_read_b128 v[134:137], v12 offset:19456
	ds_read_b128 v[138:141], v12 offset:20480
	ds_read_b128 v[142:145], v12 offset:21504
	ds_read_b128 v[146:149], v12 offset:22528
	ds_read_b128 v[150:153], v12 offset:23552
	global_load_lds_dwordx4 v[20:21], off
	v_lshl_add_u64 v[20:21], v[4:5], 0, s[86:87]
	s_mov_b32 m0, s36
	s_nop 0
	global_load_lds_dwordx4 v[20:21], off
	s_barrier
	s_waitcnt lgkmcnt(0)
	s_setprio 1
	s_waitcnt lgkmcnt(0)
	v_mfma_f32_16x16x32_bf16 v[154:157], v[66:69], v[22:25], 0
	v_mfma_f32_16x16x32_bf16 v[162:165], v[126:129], v[22:25], 0
	v_mfma_f32_16x16x32_bf16 v[170:173], v[138:141], v[22:25], 0
	v_mfma_f32_16x16x32_bf16 v[20:23], v[146:149], v[22:25], 0
	v_mfma_f32_16x16x32_bf16 v[154:157], v[122:125], v[26:29], v[154:157]
	v_mfma_f32_16x16x32_bf16 v[162:165], v[134:137], v[26:29], v[162:165]
	v_mfma_f32_16x16x32_bf16 v[170:173], v[142:145], v[26:29], v[170:173]
	v_mfma_f32_16x16x32_bf16 v[20:23], v[150:153], v[26:29], v[20:23]
	v_mfma_f32_16x16x32_bf16 v[24:27], v[146:149], v[30:33], 0
	v_mfma_f32_16x16x32_bf16 v[158:161], v[66:69], v[30:33], 0
	v_mfma_f32_16x16x32_bf16 v[166:169], v[126:129], v[30:33], 0
	v_mfma_f32_16x16x32_bf16 v[174:177], v[138:141], v[30:33], 0
	v_mfma_f32_16x16x32_bf16 v[24:27], v[150:153], v[34:37], v[24:27]
	v_mfma_f32_16x16x32_bf16 v[158:161], v[122:125], v[34:37], v[158:161]
	v_mfma_f32_16x16x32_bf16 v[166:169], v[134:137], v[34:37], v[166:169]
	v_mfma_f32_16x16x32_bf16 v[174:177], v[142:145], v[34:37], v[174:177]
	s_setprio 0
	s_barrier
	v_readfirstlane_b32 s36, v17
	v_lshl_add_u64 v[28:29], s[22:23], 0, v[0:1]
	s_mov_b32 m0, s36
	v_lshl_add_u64 v[16:17], s[22:23], 0, v[2:3]
	v_readfirstlane_b32 s22, v18
	global_load_lds_dwordx4 v[28:29], off
	s_mov_b32 m0, s22
	s_nop 0
	global_load_lds_dwordx4 v[16:17], off
	s_waitcnt vmcnt(6)
	s_barrier
	s_setprio 1
	v_mfma_f32_16x16x32_bf16 v[16:19], v[66:69], v[102:105], 0
	v_mfma_f32_16x16x32_bf16 v[28:31], v[66:69], v[110:113], 0
	v_mfma_f32_16x16x32_bf16 v[16:19], v[122:125], v[106:109], v[16:19]
	v_mfma_f32_16x16x32_bf16 v[28:31], v[122:125], v[114:117], v[28:31]
	v_mfma_f32_16x16x32_bf16 v[32:35], v[126:129], v[102:105], 0
	v_mfma_f32_16x16x32_bf16 v[122:125], v[138:141], v[102:105], 0
	v_mfma_f32_16x16x32_bf16 v[102:105], v[146:149], v[102:105], 0
	v_mfma_f32_16x16x32_bf16 v[32:35], v[134:137], v[106:109], v[32:35]
	v_mfma_f32_16x16x32_bf16 v[66:69], v[126:129], v[110:113], 0
	v_mfma_f32_16x16x32_bf16 v[122:125], v[142:145], v[106:109], v[122:125]
	v_mfma_f32_16x16x32_bf16 v[126:129], v[138:141], v[110:113], 0
	v_mfma_f32_16x16x32_bf16 v[102:105], v[150:153], v[106:109], v[102:105]
	v_mfma_f32_16x16x32_bf16 v[106:109], v[146:149], v[110:113], 0
	v_mfma_f32_16x16x32_bf16 v[66:69], v[134:137], v[114:117], v[66:69]
	v_mfma_f32_16x16x32_bf16 v[126:129], v[142:145], v[114:117], v[126:129]
	v_mfma_f32_16x16x32_bf16 v[106:109], v[150:153], v[114:117], v[106:109]
	s_setprio 0
	v_or_b32_e32 v13, 0x18000, v131
	v_or_b32_e32 v227, 0x18800, v131
	s_barrier
	v_or_b32_e32 v226, 0x18400, v131
	ds_read_b128 v[110:113], v13
	ds_read_b128 v[114:117], v226
	v_or_b32_e32 v228, 0x18c00, v131
	ds_read_b128 v[134:137], v227
	ds_read_b128 v[138:141], v228
	v_readfirstlane_b32 s22, v14
	v_lshl_add_u64 v[36:37], s[20:21], 0, v[0:1]
	s_mov_b32 m0, s22
	ds_read_b128 v[142:145], v12 offset:32768
	ds_read_b128 v[146:149], v12 offset:33792
	ds_read_b128 v[150:153], v12 offset:34816
	ds_read_b128 v[182:185], v12 offset:35840
	ds_read_b128 v[186:189], v12 offset:36864
	ds_read_b128 v[190:193], v12 offset:37888
	ds_read_b128 v[194:197], v12 offset:38912
	ds_read_b128 v[198:201], v12 offset:39936
	global_load_lds_dwordx4 v[36:37], off
	v_lshl_add_u64 v[36:37], s[20:21], 0, v[2:3]
	v_readfirstlane_b32 s20, v15
	s_mov_b32 m0, s20
	s_nop 0
	global_load_lds_dwordx4 v[36:37], off
	s_waitcnt lgkmcnt(8)
	s_barrier
	s_waitcnt lgkmcnt(0)
	s_setprio 1
	s_waitcnt lgkmcnt(0)
	v_mfma_f32_16x16x32_bf16 v[70:73], v[142:145], v[110:113], v[70:73]
	v_mfma_f32_16x16x32_bf16 v[74:77], v[142:145], v[134:137], v[74:77]
	v_mfma_f32_16x16x32_bf16 v[78:81], v[150:153], v[110:113], v[78:81]
	v_mfma_f32_16x16x32_bf16 v[82:85], v[150:153], v[134:137], v[82:85]
	v_mfma_f32_16x16x32_bf16 v[86:89], v[186:189], v[110:113], v[86:89]
	v_mfma_f32_16x16x32_bf16 v[90:93], v[186:189], v[134:137], v[90:93]
	v_mfma_f32_16x16x32_bf16 v[94:97], v[194:197], v[110:113], v[94:97]
	v_mfma_f32_16x16x32_bf16 v[98:101], v[194:197], v[134:137], v[98:101]
	v_mfma_f32_16x16x32_bf16 v[70:73], v[146:149], v[114:117], v[70:73]
	v_mfma_f32_16x16x32_bf16 v[74:77], v[146:149], v[138:141], v[74:77]
	v_mfma_f32_16x16x32_bf16 v[78:81], v[182:185], v[114:117], v[78:81]
	v_mfma_f32_16x16x32_bf16 v[82:85], v[182:185], v[138:141], v[82:85]
	v_mfma_f32_16x16x32_bf16 v[86:89], v[190:193], v[114:117], v[86:89]
	v_mfma_f32_16x16x32_bf16 v[90:93], v[190:193], v[138:141], v[90:93]
	v_mfma_f32_16x16x32_bf16 v[94:97], v[198:201], v[114:117], v[94:97]
	v_mfma_f32_16x16x32_bf16 v[98:101], v[198:201], v[138:141], v[98:101]
	s_setprio 0
	s_barrier
	s_mov_b32 m0, s35
	v_or_b32_e32 v242, 0x1c000, v131
	v_or_b32_e32 v250, 0x1c800, v131
	v_lshl_add_u64 v[8:9], v[8:9], 0, s[66:67]
	v_or_b32_e32 v246, 0x1c400, v131
	ds_read_b128 v[202:205], v242
	ds_read_b128 v[206:209], v246
	v_or_b32_e32 v131, 0x1cc00, v131
	ds_read_b128 v[210:213], v250
	ds_read_b128 v[222:225], v131
	global_load_lds_dwordx4 v[8:9], off
	v_lshl_add_u64 v[8:9], v[10:11], 0, s[66:67]
	s_mov_b32 m0, s34
	s_nop 0
	global_load_lds_dwordx4 v[8:9], off
	s_barrier
	s_waitcnt lgkmcnt(0)
	s_setprio 1
	s_waitcnt lgkmcnt(0)
	v_mfma_f32_16x16x32_bf16 v[8:11], v[142:145], v[202:205], v[118:121]
	v_mfma_f32_16x16x32_bf16 v[36:39], v[142:145], v[210:213], v[38:41]
	v_mfma_f32_16x16x32_bf16 v[40:43], v[150:153], v[202:205], v[42:45]
	v_mfma_f32_16x16x32_bf16 v[44:47], v[150:153], v[210:213], v[46:49]
	v_mfma_f32_16x16x32_bf16 v[48:51], v[186:189], v[202:205], v[50:53]
	v_mfma_f32_16x16x32_bf16 v[52:55], v[186:189], v[210:213], v[54:57]
	v_mfma_f32_16x16x32_bf16 v[56:59], v[194:197], v[202:205], v[58:61]
	v_mfma_f32_16x16x32_bf16 v[60:63], v[194:197], v[210:213], v[62:65]
	v_mfma_f32_16x16x32_bf16 v[8:11], v[146:149], v[206:209], v[8:11]
	v_mfma_f32_16x16x32_bf16 v[36:39], v[146:149], v[222:225], v[36:39]
	v_mfma_f32_16x16x32_bf16 v[40:43], v[182:185], v[206:209], v[40:43]
	v_mfma_f32_16x16x32_bf16 v[44:47], v[182:185], v[222:225], v[44:47]
	v_mfma_f32_16x16x32_bf16 v[48:51], v[190:193], v[206:209], v[48:51]
	v_mfma_f32_16x16x32_bf16 v[52:55], v[190:193], v[222:225], v[52:55]
	v_mfma_f32_16x16x32_bf16 v[56:59], v[198:201], v[206:209], v[56:59]
	v_mfma_f32_16x16x32_bf16 v[60:63], v[198:201], v[222:225], v[60:63]
	s_setprio 0
	s_mov_b32 m0, s30
	v_lshl_add_u64 v[6:7], v[6:7], 0, s[66:67]
	s_barrier
	ds_read_b128 v[118:121], v12 offset:49152
	ds_read_b128 v[142:145], v12 offset:50176
	ds_read_b128 v[146:149], v12 offset:51200
	ds_read_b128 v[150:153], v12 offset:52224
	ds_read_b128 v[182:185], v12 offset:53248
	ds_read_b128 v[186:189], v12 offset:54272
	ds_read_b128 v[190:193], v12 offset:55296
	ds_read_b128 v[194:197], v12 offset:56320
	global_load_lds_dwordx4 v[6:7], off
	v_lshl_add_u64 v[4:5], v[4:5], 0, s[66:67]
	s_mov_b32 m0, s29
	s_nop 0
	global_load_lds_dwordx4 v[4:5], off
	s_barrier
	s_waitcnt lgkmcnt(0)
	s_setprio 1
	s_waitcnt lgkmcnt(0)
	v_mfma_f32_16x16x32_bf16 v[4:7], v[118:121], v[110:113], v[154:157]
	v_mfma_f32_16x16x32_bf16 v[20:23], v[190:193], v[110:113], v[20:23]
	v_mfma_f32_16x16x32_bf16 v[24:27], v[190:193], v[134:137], v[24:27]
	v_mfma_f32_16x16x32_bf16 v[4:7], v[142:145], v[114:117], v[4:7]
	v_mfma_f32_16x16x32_bf16 v[154:157], v[118:121], v[134:137], v[158:161]
	v_mfma_f32_16x16x32_bf16 v[158:161], v[146:149], v[110:113], v[162:165]
	v_mfma_f32_16x16x32_bf16 v[162:165], v[146:149], v[134:137], v[166:169]
	v_mfma_f32_16x16x32_bf16 v[166:169], v[182:185], v[110:113], v[170:173]
	v_mfma_f32_16x16x32_bf16 v[170:173], v[182:185], v[134:137], v[174:177]
	v_mfma_f32_16x16x32_bf16 v[20:23], v[194:197], v[114:117], v[20:23]
	v_mfma_f32_16x16x32_bf16 v[24:27], v[194:197], v[138:141], v[24:27]
	v_mfma_f32_16x16x32_bf16 v[154:157], v[142:145], v[138:141], v[154:157]
	v_mfma_f32_16x16x32_bf16 v[158:161], v[150:153], v[114:117], v[158:161]
	v_mfma_f32_16x16x32_bf16 v[162:165], v[150:153], v[138:141], v[162:165]
	v_mfma_f32_16x16x32_bf16 v[166:169], v[186:189], v[114:117], v[166:169]
	v_mfma_f32_16x16x32_bf16 v[170:173], v[186:189], v[138:141], v[170:173]
	s_setprio 0
	s_barrier
	s_mov_b32 m0, s15
	v_lshl_add_u64 v[14:15], s[18:19], 0, v[0:1]
	global_load_lds_dwordx4 v[14:15], off
	v_lshl_add_u64 v[14:15], s[18:19], 0, v[2:3]
	s_mov_b32 m0, s2
	s_nop 0
	global_load_lds_dwordx4 v[14:15], off
	s_waitcnt vmcnt(6)
	s_barrier
	s_setprio 1
	v_mfma_f32_16x16x32_bf16 v[14:17], v[118:121], v[202:205], v[16:19]
	v_mfma_f32_16x16x32_bf16 v[28:31], v[118:121], v[210:213], v[28:31]
	v_mfma_f32_16x16x32_bf16 v[32:35], v[146:149], v[202:205], v[32:35]
	v_mfma_f32_16x16x32_bf16 v[64:67], v[146:149], v[210:213], v[66:69]
	v_mfma_f32_16x16x32_bf16 v[110:113], v[182:185], v[202:205], v[122:125]
	v_mfma_f32_16x16x32_bf16 v[114:117], v[182:185], v[210:213], v[126:129]
	v_mfma_f32_16x16x32_bf16 v[102:105], v[190:193], v[202:205], v[102:105]
	v_mfma_f32_16x16x32_bf16 v[106:109], v[190:193], v[210:213], v[106:109]
	v_mfma_f32_16x16x32_bf16 v[14:17], v[142:145], v[206:209], v[14:17]
	v_mfma_f32_16x16x32_bf16 v[28:31], v[142:145], v[222:225], v[28:31]
	v_mfma_f32_16x16x32_bf16 v[32:35], v[150:153], v[206:209], v[32:35]
	v_mfma_f32_16x16x32_bf16 v[64:67], v[150:153], v[222:225], v[64:67]
	v_mfma_f32_16x16x32_bf16 v[110:113], v[186:189], v[206:209], v[110:113]
	v_mfma_f32_16x16x32_bf16 v[114:117], v[186:189], v[222:225], v[114:117]
	v_mfma_f32_16x16x32_bf16 v[102:105], v[194:197], v[206:209], v[102:105]
	v_mfma_f32_16x16x32_bf16 v[106:109], v[194:197], v[222:225], v[106:109]
	s_setprio 0
	s_add_u32 s6, s6, 0x10180
	s_addc_u32 s7, s7, 0
	s_mov_b32 m0, s31
	v_lshl_add_u64 v[18:19], s[6:7], 0, v[0:1]
	s_barrier
	ds_read_b128 v[118:121], v133
	ds_read_b128 v[122:125], v178
	ds_read_b128 v[126:129], v179
	ds_read_b128 v[134:137], v214
	ds_read_b128 v[138:141], v12
	ds_read_b128 v[142:145], v12 offset:1024
	ds_read_b128 v[146:149], v12 offset:2048
	ds_read_b128 v[150:153], v12 offset:3072
	ds_read_b128 v[174:177], v12 offset:4096
	ds_read_b128 v[182:185], v12 offset:5120
	ds_read_b128 v[186:189], v12 offset:6144
	ds_read_b128 v[190:193], v12 offset:7168
	global_load_lds_dwordx4 v[18:19], off
	v_lshl_add_u64 v[2:3], s[6:7], 0, v[2:3]
	s_mov_b32 m0, s17
	s_nop 0
	global_load_lds_dwordx4 v[2:3], off
	s_barrier
	s_waitcnt lgkmcnt(0)
	s_setprio 1
	s_waitcnt lgkmcnt(0)
	v_mfma_f32_16x16x32_bf16 v[68:71], v[138:141], v[118:121], v[70:73]
	v_mfma_f32_16x16x32_bf16 v[72:75], v[138:141], v[126:129], v[74:77]
	v_mfma_f32_16x16x32_bf16 v[76:79], v[146:149], v[118:121], v[78:81]
	v_mfma_f32_16x16x32_bf16 v[80:83], v[146:149], v[126:129], v[82:85]
	v_mfma_f32_16x16x32_bf16 v[84:87], v[174:177], v[118:121], v[86:89]
	v_mfma_f32_16x16x32_bf16 v[88:91], v[174:177], v[126:129], v[90:93]
	v_mfma_f32_16x16x32_bf16 v[92:95], v[186:189], v[118:121], v[94:97]
	v_mfma_f32_16x16x32_bf16 v[96:99], v[186:189], v[126:129], v[98:101]
	v_mfma_f32_16x16x32_bf16 v[68:71], v[142:145], v[122:125], v[68:71]
	v_mfma_f32_16x16x32_bf16 v[72:75], v[142:145], v[134:137], v[72:75]
	v_mfma_f32_16x16x32_bf16 v[76:79], v[150:153], v[122:125], v[76:79]
	v_mfma_f32_16x16x32_bf16 v[80:83], v[150:153], v[134:137], v[80:83]
	v_mfma_f32_16x16x32_bf16 v[84:87], v[182:185], v[122:125], v[84:87]
	v_mfma_f32_16x16x32_bf16 v[88:91], v[182:185], v[134:137], v[88:91]
	v_mfma_f32_16x16x32_bf16 v[92:95], v[190:193], v[122:125], v[92:95]
	v_mfma_f32_16x16x32_bf16 v[96:99], v[190:193], v[134:137], v[96:99]
	s_setprio 0
	s_barrier
	ds_read_b128 v[194:197], v215
	ds_read_b128 v[198:201], v216
	ds_read_b128 v[202:205], v217
	ds_read_b128 v[206:209], v221
	s_barrier
	s_waitcnt lgkmcnt(0)
	s_setprio 1
	s_waitcnt lgkmcnt(3)
	v_mfma_f32_16x16x32_bf16 v[48:51], v[174:177], v[194:197], v[48:51]
	v_mfma_f32_16x16x32_bf16 v[8:11], v[138:141], v[194:197], v[8:11]
	s_waitcnt lgkmcnt(1)
	v_mfma_f32_16x16x32_bf16 v[36:39], v[138:141], v[202:205], v[36:39]
	v_mfma_f32_16x16x32_bf16 v[138:141], v[182:185], v[198:201], v[48:51]
	v_mfma_f32_16x16x32_bf16 v[48:51], v[174:177], v[202:205], v[52:55]
	v_mfma_f32_16x16x32_bf16 v[8:11], v[142:145], v[198:201], v[8:11]
	s_waitcnt lgkmcnt(0)
	v_mfma_f32_16x16x32_bf16 v[36:39], v[142:145], v[206:209], v[36:39]
	v_mfma_f32_16x16x32_bf16 v[40:43], v[146:149], v[194:197], v[40:43]
	v_mfma_f32_16x16x32_bf16 v[44:47], v[146:149], v[202:205], v[44:47]
	v_mfma_f32_16x16x32_bf16 v[142:145], v[182:185], v[206:209], v[48:51]
	v_mfma_f32_16x16x32_bf16 v[48:51], v[186:189], v[194:197], v[56:59]
	v_mfma_f32_16x16x32_bf16 v[40:43], v[150:153], v[198:201], v[40:43]
	v_mfma_f32_16x16x32_bf16 v[44:47], v[150:153], v[206:209], v[44:47]
	v_mfma_f32_16x16x32_bf16 v[146:149], v[190:193], v[198:201], v[48:51]
	v_mfma_f32_16x16x32_bf16 v[48:51], v[186:189], v[202:205], v[60:63]
	v_mfma_f32_16x16x32_bf16 v[150:153], v[190:193], v[206:209], v[48:51]
	s_setprio 0
	s_barrier
	s_nop 4
	ds_read_b128 v[48:51], v12 offset:16384
	ds_read_b128 v[52:55], v12 offset:17408
	ds_read_b128 v[56:59], v12 offset:18432
	ds_read_b128 v[60:63], v12 offset:19456
	ds_read_b128 v[174:177], v12 offset:20480
	ds_read_b128 v[182:185], v12 offset:21504
	ds_read_b128 v[186:189], v12 offset:22528
	ds_read_b128 v[190:193], v12 offset:23552
	s_waitcnt vmcnt(4)
	s_barrier
	s_waitcnt lgkmcnt(0)
	s_setprio 1
	s_waitcnt lgkmcnt(7)
	v_mfma_f32_16x16x32_bf16 v[2:5], v[48:51], v[118:121], v[4:7]
	s_waitcnt lgkmcnt(1)
	v_mfma_f32_16x16x32_bf16 v[18:21], v[186:189], v[118:121], v[20:23]
	v_mfma_f32_16x16x32_bf16 v[22:25], v[186:189], v[126:129], v[24:27]
	v_mfma_f32_16x16x32_bf16 v[2:5], v[52:55], v[122:125], v[2:5]
	v_mfma_f32_16x16x32_bf16 v[154:157], v[48:51], v[126:129], v[154:157]
	v_mfma_f32_16x16x32_bf16 v[158:161], v[56:59], v[118:121], v[158:161]
	v_mfma_f32_16x16x32_bf16 v[162:165], v[56:59], v[126:129], v[162:165]
	v_mfma_f32_16x16x32_bf16 v[166:169], v[174:177], v[118:121], v[166:169]
	v_mfma_f32_16x16x32_bf16 v[170:173], v[174:177], v[126:129], v[170:173]
	s_waitcnt lgkmcnt(0)
	v_mfma_f32_16x16x32_bf16 v[18:21], v[190:193], v[122:125], v[18:21]
	v_mfma_f32_16x16x32_bf16 v[22:25], v[190:193], v[134:137], v[22:25]
	v_mfma_f32_16x16x32_bf16 v[154:157], v[52:55], v[134:137], v[154:157]
	v_mfma_f32_16x16x32_bf16 v[158:161], v[60:63], v[122:125], v[158:161]
	v_mfma_f32_16x16x32_bf16 v[162:165], v[60:63], v[134:137], v[162:165]
	v_mfma_f32_16x16x32_bf16 v[166:169], v[182:185], v[122:125], v[166:169]
	v_mfma_f32_16x16x32_bf16 v[170:173], v[182:185], v[134:137], v[170:173]
	s_setprio 0
	s_setprio 1
	v_mfma_f32_16x16x32_bf16 v[26:29], v[48:51], v[202:205], v[28:31]
	v_mfma_f32_16x16x32_bf16 v[30:33], v[56:59], v[194:197], v[32:35]
	v_mfma_f32_16x16x32_bf16 v[134:137], v[60:63], v[198:201], v[30:33]
	v_mfma_f32_16x16x32_bf16 v[30:33], v[56:59], v[202:205], v[64:67]
	v_mfma_f32_16x16x32_bf16 v[210:213], v[60:63], v[206:209], v[30:33]
	v_mfma_f32_16x16x32_bf16 v[30:33], v[174:177], v[194:197], v[110:113]
	v_mfma_f32_16x16x32_bf16 v[222:225], v[182:185], v[198:201], v[30:33]
	v_mfma_f32_16x16x32_bf16 v[30:33], v[174:177], v[202:205], v[114:117]
	v_mfma_f32_16x16x32_bf16 v[14:17], v[48:51], v[194:197], v[14:17]
	v_mfma_f32_16x16x32_bf16 v[174:177], v[182:185], v[206:209], v[30:33]
	v_mfma_f32_16x16x32_bf16 v[30:33], v[186:189], v[194:197], v[102:105]
	v_mfma_f32_16x16x32_bf16 v[14:17], v[52:55], v[198:201], v[14:17]
	v_mfma_f32_16x16x32_bf16 v[26:29], v[52:55], v[206:209], v[26:29]
	v_mfma_f32_16x16x32_bf16 v[182:185], v[190:193], v[198:201], v[30:33]
	v_mfma_f32_16x16x32_bf16 v[30:33], v[186:189], v[202:205], v[106:109]
	v_mfma_f32_16x16x32_bf16 v[186:189], v[190:193], v[206:209], v[30:33]
	s_setprio 0
	s_barrier
	s_nop 4
	ds_read_b128 v[30:33], v13
	ds_read_b128 v[190:193], v226
	ds_read_b128 v[194:197], v227
	ds_read_b128 v[198:201], v228
	ds_read_b128 v[48:51], v12 offset:32768
	ds_read_b128 v[52:55], v12 offset:33792
	ds_read_b128 v[202:205], v12 offset:34816
	ds_read_b128 v[206:209], v12 offset:35840
	ds_read_b128 v[226:229], v12 offset:36864
	ds_read_b128 v[230:233], v12 offset:37888
	ds_read_b128 v[234:237], v12 offset:38912
	ds_read_b128 v[238:241], v12 offset:39936
	s_waitcnt vmcnt(2)
	s_barrier
	s_waitcnt lgkmcnt(0)
	s_setprio 1
	s_waitcnt lgkmcnt(7)
	v_mfma_f32_16x16x32_bf16 v[56:59], v[48:51], v[30:33], v[68:71]
	s_waitcnt lgkmcnt(6)
	v_mfma_f32_16x16x32_bf16 v[66:69], v[52:55], v[190:193], v[56:59]
	v_mfma_f32_16x16x32_bf16 v[56:59], v[48:51], v[194:197], v[72:75]
	v_mfma_f32_16x16x32_bf16 v[126:129], v[52:55], v[198:201], v[56:59]
	s_waitcnt lgkmcnt(5)
	v_mfma_f32_16x16x32_bf16 v[56:59], v[202:205], v[30:33], v[76:79]
	s_waitcnt lgkmcnt(4)
	v_mfma_f32_16x16x32_bf16 v[118:121], v[206:209], v[190:193], v[56:59]
	v_mfma_f32_16x16x32_bf16 v[56:59], v[202:205], v[194:197], v[80:83]
	v_mfma_f32_16x16x32_bf16 v[122:125], v[206:209], v[198:201], v[56:59]
	s_waitcnt lgkmcnt(3)
	v_mfma_f32_16x16x32_bf16 v[56:59], v[226:229], v[30:33], v[84:87]
	s_waitcnt lgkmcnt(2)
	v_mfma_f32_16x16x32_bf16 v[110:113], v[230:233], v[190:193], v[56:59]
	v_mfma_f32_16x16x32_bf16 v[56:59], v[226:229], v[194:197], v[88:91]
	v_mfma_f32_16x16x32_bf16 v[114:117], v[230:233], v[198:201], v[56:59]
	s_waitcnt lgkmcnt(1)
	v_mfma_f32_16x16x32_bf16 v[56:59], v[234:237], v[30:33], v[92:95]
	s_waitcnt lgkmcnt(0)
	v_mfma_f32_16x16x32_bf16 v[102:105], v[238:241], v[190:193], v[56:59]
	v_mfma_f32_16x16x32_bf16 v[56:59], v[234:237], v[194:197], v[96:99]
	v_mfma_f32_16x16x32_bf16 v[106:109], v[238:241], v[198:201], v[56:59]
	s_setprio 0
	s_barrier
	ds_read_b128 v[242:245], v242
	ds_read_b128 v[246:249], v246
	ds_read_b128 v[250:253], v250
	ds_read_b128 v[214:217], v131
	s_waitcnt vmcnt(0)
	s_barrier
	s_waitcnt lgkmcnt(0)
	s_setprio 1
	s_waitcnt lgkmcnt(3)
	v_mfma_f32_16x16x32_bf16 v[6:9], v[48:51], v[242:245], v[8:11]
	s_waitcnt lgkmcnt(2)
	v_mfma_f32_16x16x32_bf16 v[62:65], v[52:55], v[246:249], v[6:9]
	s_waitcnt lgkmcnt(1)
	v_mfma_f32_16x16x32_bf16 v[6:9], v[48:51], v[250:253], v[36:39]
	s_waitcnt lgkmcnt(0)
	v_mfma_f32_16x16x32_bf16 v[58:61], v[52:55], v[214:217], v[6:9]
	v_mfma_f32_16x16x32_bf16 v[6:9], v[202:205], v[242:245], v[40:43]
	v_mfma_f32_16x16x32_bf16 v[54:57], v[206:209], v[246:249], v[6:9]
	v_mfma_f32_16x16x32_bf16 v[6:9], v[202:205], v[250:253], v[44:47]
	v_mfma_f32_16x16x32_bf16 v[50:53], v[206:209], v[214:217], v[6:9]
	v_mfma_f32_16x16x32_bf16 v[6:9], v[226:229], v[242:245], v[138:141]
	v_mfma_f32_16x16x32_bf16 v[46:49], v[230:233], v[246:249], v[6:9]
	v_mfma_f32_16x16x32_bf16 v[6:9], v[226:229], v[250:253], v[142:145]
	v_mfma_f32_16x16x32_bf16 v[42:45], v[230:233], v[214:217], v[6:9]
	v_mfma_f32_16x16x32_bf16 v[6:9], v[234:237], v[242:245], v[146:149]
	v_mfma_f32_16x16x32_bf16 v[38:41], v[238:241], v[246:249], v[6:9]
	v_mfma_f32_16x16x32_bf16 v[6:9], v[234:237], v[250:253], v[150:153]
	v_mfma_f32_16x16x32_bf16 v[34:37], v[238:241], v[214:217], v[6:9]
	s_setprio 0
	s_barrier
	s_nop 4
	ds_read_b128 v[6:9], v12 offset:49152
	ds_read_b128 v[138:141], v12 offset:50176
	ds_read_b128 v[142:145], v12 offset:51200
	ds_read_b128 v[146:149], v12 offset:52224
	ds_read_b128 v[150:153], v12 offset:53248
	ds_read_b128 v[202:205], v12 offset:54272
	ds_read_b128 v[206:209], v12 offset:55296
	ds_read_b128 v[226:229], v12 offset:56320
	s_barrier
	s_waitcnt lgkmcnt(0)
	s_setprio 1
	s_waitcnt lgkmcnt(7)
	v_mfma_f32_16x16x32_bf16 v[2:5], v[6:9], v[30:33], v[2:5]
	s_waitcnt lgkmcnt(6)
	v_mfma_f32_16x16x32_bf16 v[94:97], v[138:141], v[190:193], v[2:5]
	v_mfma_f32_16x16x32_bf16 v[2:5], v[6:9], v[194:197], v[154:157]
	v_mfma_f32_16x16x32_bf16 v[98:101], v[138:141], v[198:201], v[2:5]
	s_waitcnt lgkmcnt(5)
	v_mfma_f32_16x16x32_bf16 v[2:5], v[142:145], v[30:33], v[158:161]
	s_waitcnt lgkmcnt(4)
	v_mfma_f32_16x16x32_bf16 v[86:89], v[146:149], v[190:193], v[2:5]
	v_mfma_f32_16x16x32_bf16 v[2:5], v[142:145], v[194:197], v[162:165]
	v_mfma_f32_16x16x32_bf16 v[90:93], v[146:149], v[198:201], v[2:5]
	s_waitcnt lgkmcnt(3)
	v_mfma_f32_16x16x32_bf16 v[2:5], v[150:153], v[30:33], v[166:169]
	s_waitcnt lgkmcnt(2)
	v_mfma_f32_16x16x32_bf16 v[78:81], v[202:205], v[190:193], v[2:5]
	v_mfma_f32_16x16x32_bf16 v[2:5], v[150:153], v[194:197], v[170:173]
	v_mfma_f32_16x16x32_bf16 v[82:85], v[202:205], v[198:201], v[2:5]
	s_waitcnt lgkmcnt(1)
	v_mfma_f32_16x16x32_bf16 v[2:5], v[206:209], v[30:33], v[18:21]
	s_waitcnt lgkmcnt(0)
	v_mfma_f32_16x16x32_bf16 v[70:73], v[226:229], v[190:193], v[2:5]
	v_mfma_f32_16x16x32_bf16 v[2:5], v[206:209], v[194:197], v[22:25]
	v_mfma_f32_16x16x32_bf16 v[74:77], v[226:229], v[198:201], v[2:5]
	s_setprio 0
	s_setprio 1
	v_mfma_f32_16x16x32_bf16 v[2:5], v[6:9], v[242:245], v[14:17]
	v_mfma_f32_16x16x32_bf16 v[30:33], v[138:141], v[246:249], v[2:5]
	v_mfma_f32_16x16x32_bf16 v[2:5], v[6:9], v[250:253], v[26:29]
	v_mfma_f32_16x16x32_bf16 v[26:29], v[138:141], v[214:217], v[2:5]
	v_mfma_f32_16x16x32_bf16 v[2:5], v[142:145], v[242:245], v[134:137]
	v_mfma_f32_16x16x32_bf16 v[22:25], v[146:149], v[246:249], v[2:5]
	v_mfma_f32_16x16x32_bf16 v[2:5], v[142:145], v[250:253], v[210:213]
	v_mfma_f32_16x16x32_bf16 v[18:21], v[146:149], v[214:217], v[2:5]
	v_mfma_f32_16x16x32_bf16 v[2:5], v[150:153], v[242:245], v[222:225]
	v_mfma_f32_16x16x32_bf16 v[14:17], v[202:205], v[246:249], v[2:5]
	v_mfma_f32_16x16x32_bf16 v[2:5], v[150:153], v[250:253], v[174:177]
	v_mfma_f32_16x16x32_bf16 v[10:13], v[202:205], v[214:217], v[2:5]
	v_mfma_f32_16x16x32_bf16 v[2:5], v[206:209], v[242:245], v[182:185]
	v_mfma_f32_16x16x32_bf16 v[6:9], v[226:229], v[246:249], v[2:5]
	v_mfma_f32_16x16x32_bf16 v[2:5], v[206:209], v[250:253], v[186:189]
	v_mfma_f32_16x16x32_bf16 v[2:5], v[226:229], v[214:217], v[2:5]
	s_setprio 0
	v_cmp_gt_u32_e32 vcc, s39, v130
	s_barrier
	s_and_saveexec_b64 s[6:7], vcc
	s_cbranch_execz .LBB0_971
	s_barrier

.LBB0_1093:
	s_or_b64 exec, exec, s[18:19]
	v_add_u32_e32 v24, 0x18000, v13
	v_lshl_add_u64 v[8:9], s[16:17], 0, v[0:1]
	v_mov_b32_e32 v3, v1
	v_readfirstlane_b32 s31, v24
	v_add_u32_e32 v24, 0x1a000, v13
	v_lshl_add_u64 v[10:11], s[16:17], 0, v[2:3]
	v_lshl_add_u64 v[22:23], v[8:9], 0, s[84:85]
	s_mov_b32 m0, s31
	v_readfirstlane_b32 s30, v24
	v_add_u32_e32 v24, 0x8000, v13
	v_lshl_add_u64 v[6:7], s[6:7], 0, v[0:1]
	s_waitcnt vmcnt(4)
	s_barrier
	global_load_lds_dwordx4 v[22:23], off
	v_lshl_add_u64 v[22:23], v[10:11], 0, s[84:85]
	s_mov_b32 m0, s30
	v_readfirstlane_b32 s28, v24
	v_add_u32_e32 v24, 0xa000, v13
	v_lshl_add_u64 v[4:5], s[6:7], 0, v[2:3]
	global_load_lds_dwordx4 v[22:23], off
	v_lshl_add_u64 v[22:23], v[6:7], 0, s[84:85]
	s_mov_b32 m0, s28
	v_readfirstlane_b32 s27, v24
	s_add_u32 s18, s16, 0x10080
	v_add_u32_e32 v24, 0x1c000, v13
	global_load_lds_dwordx4 v[22:23], off
	v_lshl_add_u64 v[22:23], v[4:5], 0, s[84:85]
	s_mov_b32 m0, s27
	s_addc_u32 s19, s17, 0
	v_readfirstlane_b32 s15, v24
	v_add_u32_e32 v24, 0x1e000, v13
	global_load_lds_dwordx4 v[22:23], off
	v_lshl_add_u64 v[22:23], s[18:19], 0, v[0:1]
	s_mov_b32 m0, s15
	v_readfirstlane_b32 s2, v24
	global_load_lds_dwordx4 v[22:23], off
	v_lshl_add_u64 v[22:23], s[18:19], 0, v[2:3]
	s_mov_b32 m0, s2
	s_add_u32 s34, s6, 0x10080
	global_load_lds_dwordx4 v[22:23], off
	v_and_b32_e32 v22, 15, v12
	v_and_b32_e32 v23, 48, v12
	v_lshlrev_b32_e32 v12, 2, v12
	v_lshlrev_b32_e32 v22, 6, v22
	v_and_b32_e32 v12, 32, v12
	v_or_b32_e32 v24, v22, v23
	v_bitop3_b32 v22, v22, v12, v23 bitop3:0x36
	v_lshlrev_b32_e32 v23, 6, v130
	v_and_or_b32 v131, v23, s36, v22
	v_lshlrev_b32_e32 v21, 13, v21
	s_addc_u32 s35, s7, 0
	v_or_b32_e32 v133, 0x10000, v131
	v_or_b32_e32 v179, 0x10800, v131
	v_bitop3_b32 v12, v24, v21, v12 bitop3:0xde
	s_waitcnt vmcnt(6)
	s_barrier
	s_add_u32 s20, s16, 0x10100
	v_or_b32_e32 v178, 0x10400, v131
	ds_read_b128 v[22:25], v133
	ds_read_b128 v[26:29], v178
	v_or_b32_e32 v221, 0x10c00, v131
	ds_read_b128 v[30:33], v179
	ds_read_b128 v[34:37], v221
	s_addc_u32 s21, s17, 0
	s_add_u32 s18, s6, 0x10100
	s_addc_u32 s19, s7, 0
	s_add_u32 s16, s16, 0x10180
	s_addc_u32 s17, s17, 0
	v_add_u32_e32 v21, 0xc000, v13
	v_lshl_add_u64 v[70:71], s[34:35], 0, v[0:1]
	v_readfirstlane_b32 s29, v21
	v_add_u32_e32 v21, 0xe000, v13
	s_mov_b32 m0, s29
	v_readfirstlane_b32 s26, v21
	ds_read_b128 v[38:41], v12
	ds_read_b128 v[42:45], v12 offset:1024
	ds_read_b128 v[46:49], v12 offset:2048
	ds_read_b128 v[50:53], v12 offset:3072
	ds_read_b128 v[54:57], v12 offset:4096
	ds_read_b128 v[58:61], v12 offset:5120
	ds_read_b128 v[62:65], v12 offset:6144
	ds_read_b128 v[66:69], v12 offset:7168
	global_load_lds_dwordx4 v[70:71], off
	v_lshl_add_u64 v[70:71], s[34:35], 0, v[2:3]
	s_mov_b32 m0, s26
	s_nop 0
	global_load_lds_dwordx4 v[70:71], off
	s_waitcnt lgkmcnt(8)
	s_barrier
	s_waitcnt lgkmcnt(0)
	s_setprio 1
	s_waitcnt lgkmcnt(0)
	v_mfma_f32_16x16x32_bf16 v[70:73], v[38:41], v[22:25], 0
	v_mfma_f32_16x16x32_bf16 v[74:77], v[38:41], v[30:33], 0
	v_mfma_f32_16x16x32_bf16 v[78:81], v[46:49], v[22:25], 0
	v_mfma_f32_16x16x32_bf16 v[82:85], v[46:49], v[30:33], 0
	v_mfma_f32_16x16x32_bf16 v[86:89], v[54:57], v[22:25], 0
	v_mfma_f32_16x16x32_bf16 v[90:93], v[54:57], v[30:33], 0
	v_mfma_f32_16x16x32_bf16 v[94:97], v[62:65], v[22:25], 0
	v_mfma_f32_16x16x32_bf16 v[98:101], v[62:65], v[30:33], 0
	v_mfma_f32_16x16x32_bf16 v[70:73], v[42:45], v[26:29], v[70:73]
	v_mfma_f32_16x16x32_bf16 v[74:77], v[42:45], v[34:37], v[74:77]
	v_mfma_f32_16x16x32_bf16 v[78:81], v[50:53], v[26:29], v[78:81]
	v_mfma_f32_16x16x32_bf16 v[82:85], v[50:53], v[34:37], v[82:85]
	v_mfma_f32_16x16x32_bf16 v[86:89], v[58:61], v[26:29], v[86:89]
	v_mfma_f32_16x16x32_bf16 v[90:93], v[58:61], v[34:37], v[90:93]
	v_mfma_f32_16x16x32_bf16 v[94:97], v[66:69], v[26:29], v[94:97]
	v_mfma_f32_16x16x32_bf16 v[98:101], v[66:69], v[34:37], v[98:101]
	s_setprio 0
	s_barrier
	v_readfirstlane_b32 s34, v19
	v_or_b32_e32 v222, 0x14000, v131
	v_or_b32_e32 v224, 0x14800, v131
	v_lshl_add_u64 v[118:119], v[8:9], 0, s[86:87]
	s_mov_b32 m0, s34
	v_readfirstlane_b32 s34, v20
	v_or_b32_e32 v223, 0x14400, v131
	ds_read_b128 v[102:105], v222
	ds_read_b128 v[106:109], v223
	v_or_b32_e32 v225, 0x14c00, v131
	ds_read_b128 v[110:113], v224
	ds_read_b128 v[114:117], v225
	global_load_lds_dwordx4 v[118:119], off
	v_lshl_add_u64 v[118:119], v[10:11], 0, s[86:87]
	s_mov_b32 m0, s34
	s_nop 0
	global_load_lds_dwordx4 v[118:119], off
	s_barrier
	s_waitcnt lgkmcnt(0)
	s_setprio 1
	s_waitcnt lgkmcnt(0)
	v_mfma_f32_16x16x32_bf16 v[118:121], v[38:41], v[102:105], 0
	v_mfma_f32_16x16x32_bf16 v[38:41], v[38:41], v[110:113], 0
	v_mfma_f32_16x16x32_bf16 v[118:121], v[42:45], v[106:109], v[118:121]
	v_mfma_f32_16x16x32_bf16 v[38:41], v[42:45], v[114:117], v[38:41]
	v_mfma_f32_16x16x32_bf16 v[42:45], v[46:49], v[102:105], 0
	v_mfma_f32_16x16x32_bf16 v[46:49], v[46:49], v[110:113], 0
	v_mfma_f32_16x16x32_bf16 v[42:45], v[50:53], v[106:109], v[42:45]
	v_mfma_f32_16x16x32_bf16 v[46:49], v[50:53], v[114:117], v[46:49]
	v_mfma_f32_16x16x32_bf16 v[50:53], v[54:57], v[102:105], 0
	v_mfma_f32_16x16x32_bf16 v[54:57], v[54:57], v[110:113], 0
	v_mfma_f32_16x16x32_bf16 v[50:53], v[58:61], v[106:109], v[50:53]
	v_mfma_f32_16x16x32_bf16 v[54:57], v[58:61], v[114:117], v[54:57]
	v_mfma_f32_16x16x32_bf16 v[58:61], v[62:65], v[102:105], 0
	v_mfma_f32_16x16x32_bf16 v[62:65], v[62:65], v[110:113], 0
	v_mfma_f32_16x16x32_bf16 v[58:61], v[66:69], v[106:109], v[58:61]
	v_mfma_f32_16x16x32_bf16 v[62:65], v[66:69], v[114:117], v[62:65]
	s_setprio 0
	v_readfirstlane_b32 s34, v13
	v_lshl_add_u64 v[20:21], v[6:7], 0, s[86:87]
	s_mov_b32 m0, s34
	v_readfirstlane_b32 s34, v16
	s_barrier
	ds_read_b128 v[66:69], v12 offset:16384
	ds_read_b128 v[122:125], v12 offset:17408
	ds_read_b128 v[126:129], v12 offset:18432
	ds_read_b128 v[134:137], v12 offset:19456
	ds_read_b128 v[138:141], v12 offset:20480
	ds_read_b128 v[142:145], v12 offset:21504
	ds_read_b128 v[146:149], v12 offset:22528
	ds_read_b128 v[150:153], v12 offset:23552
	global_load_lds_dwordx4 v[20:21], off
	v_lshl_add_u64 v[20:21], v[4:5], 0, s[86:87]
	s_mov_b32 m0, s34
	s_nop 0
	global_load_lds_dwordx4 v[20:21], off
	s_barrier
	s_waitcnt lgkmcnt(0)
	s_setprio 1
	s_waitcnt lgkmcnt(0)
	v_mfma_f32_16x16x32_bf16 v[154:157], v[66:69], v[22:25], 0
	v_mfma_f32_16x16x32_bf16 v[162:165], v[126:129], v[22:25], 0
	v_mfma_f32_16x16x32_bf16 v[170:173], v[138:141], v[22:25], 0
	v_mfma_f32_16x16x32_bf16 v[20:23], v[146:149], v[22:25], 0
	v_mfma_f32_16x16x32_bf16 v[154:157], v[122:125], v[26:29], v[154:157]
	v_mfma_f32_16x16x32_bf16 v[162:165], v[134:137], v[26:29], v[162:165]
	v_mfma_f32_16x16x32_bf16 v[170:173], v[142:145], v[26:29], v[170:173]
	v_mfma_f32_16x16x32_bf16 v[20:23], v[150:153], v[26:29], v[20:23]
	v_mfma_f32_16x16x32_bf16 v[24:27], v[146:149], v[30:33], 0
	v_mfma_f32_16x16x32_bf16 v[158:161], v[66:69], v[30:33], 0
	v_mfma_f32_16x16x32_bf16 v[166:169], v[126:129], v[30:33], 0
	v_mfma_f32_16x16x32_bf16 v[174:177], v[138:141], v[30:33], 0
	v_mfma_f32_16x16x32_bf16 v[24:27], v[150:153], v[34:37], v[24:27]
	v_mfma_f32_16x16x32_bf16 v[158:161], v[122:125], v[34:37], v[158:161]
	v_mfma_f32_16x16x32_bf16 v[166:169], v[134:137], v[34:37], v[166:169]
	v_mfma_f32_16x16x32_bf16 v[174:177], v[142:145], v[34:37], v[174:177]
	s_setprio 0
	s_barrier
	v_readfirstlane_b32 s34, v17
	v_lshl_add_u64 v[28:29], s[20:21], 0, v[0:1]
	s_mov_b32 m0, s34
	v_lshl_add_u64 v[16:17], s[20:21], 0, v[2:3]
	v_readfirstlane_b32 s20, v18
	global_load_lds_dwordx4 v[28:29], off
	s_mov_b32 m0, s20
	s_nop 0
	global_load_lds_dwordx4 v[16:17], off
	s_waitcnt vmcnt(6)
	s_barrier
	s_setprio 1
	v_mfma_f32_16x16x32_bf16 v[16:19], v[66:69], v[102:105], 0
	v_mfma_f32_16x16x32_bf16 v[28:31], v[66:69], v[110:113], 0
	v_mfma_f32_16x16x32_bf16 v[16:19], v[122:125], v[106:109], v[16:19]
	v_mfma_f32_16x16x32_bf16 v[28:31], v[122:125], v[114:117], v[28:31]
	v_mfma_f32_16x16x32_bf16 v[32:35], v[126:129], v[102:105], 0
	v_mfma_f32_16x16x32_bf16 v[122:125], v[138:141], v[102:105], 0
	v_mfma_f32_16x16x32_bf16 v[102:105], v[146:149], v[102:105], 0
	v_mfma_f32_16x16x32_bf16 v[32:35], v[134:137], v[106:109], v[32:35]
	v_mfma_f32_16x16x32_bf16 v[66:69], v[126:129], v[110:113], 0
	v_mfma_f32_16x16x32_bf16 v[122:125], v[142:145], v[106:109], v[122:125]
	v_mfma_f32_16x16x32_bf16 v[126:129], v[138:141], v[110:113], 0
	v_mfma_f32_16x16x32_bf16 v[102:105], v[150:153], v[106:109], v[102:105]
	v_mfma_f32_16x16x32_bf16 v[106:109], v[146:149], v[110:113], 0
	v_mfma_f32_16x16x32_bf16 v[66:69], v[134:137], v[114:117], v[66:69]
	v_mfma_f32_16x16x32_bf16 v[126:129], v[142:145], v[114:117], v[126:129]
	v_mfma_f32_16x16x32_bf16 v[106:109], v[150:153], v[114:117], v[106:109]
	s_setprio 0
	v_or_b32_e32 v13, 0x18000, v131
	v_or_b32_e32 v227, 0x18800, v131
	s_barrier
	v_or_b32_e32 v226, 0x18400, v131
	ds_read_b128 v[110:113], v13
	ds_read_b128 v[114:117], v226
	v_or_b32_e32 v228, 0x18c00, v131
	ds_read_b128 v[134:137], v227
	ds_read_b128 v[138:141], v228
	v_readfirstlane_b32 s20, v14
	v_lshl_add_u64 v[36:37], s[18:19], 0, v[0:1]
	s_mov_b32 m0, s20
	ds_read_b128 v[142:145], v12 offset:32768
	ds_read_b128 v[146:149], v12 offset:33792
	ds_read_b128 v[150:153], v12 offset:34816
	ds_read_b128 v[182:185], v12 offset:35840
	ds_read_b128 v[186:189], v12 offset:36864
	ds_read_b128 v[190:193], v12 offset:37888
	ds_read_b128 v[194:197], v12 offset:38912
	ds_read_b128 v[198:201], v12 offset:39936
	global_load_lds_dwordx4 v[36:37], off
	v_lshl_add_u64 v[36:37], s[18:19], 0, v[2:3]
	v_readfirstlane_b32 s18, v15
	s_mov_b32 m0, s18
	s_nop 0
	global_load_lds_dwordx4 v[36:37], off
	s_waitcnt lgkmcnt(8)
	s_barrier
	s_waitcnt lgkmcnt(0)
	s_setprio 1
	s_waitcnt lgkmcnt(0)
	v_mfma_f32_16x16x32_bf16 v[70:73], v[142:145], v[110:113], v[70:73]
	v_mfma_f32_16x16x32_bf16 v[74:77], v[142:145], v[134:137], v[74:77]
	v_mfma_f32_16x16x32_bf16 v[78:81], v[150:153], v[110:113], v[78:81]
	v_mfma_f32_16x16x32_bf16 v[82:85], v[150:153], v[134:137], v[82:85]
	v_mfma_f32_16x16x32_bf16 v[86:89], v[186:189], v[110:113], v[86:89]
	v_mfma_f32_16x16x32_bf16 v[90:93], v[186:189], v[134:137], v[90:93]
	v_mfma_f32_16x16x32_bf16 v[94:97], v[194:197], v[110:113], v[94:97]
	v_mfma_f32_16x16x32_bf16 v[98:101], v[194:197], v[134:137], v[98:101]
	v_mfma_f32_16x16x32_bf16 v[70:73], v[146:149], v[114:117], v[70:73]
	v_mfma_f32_16x16x32_bf16 v[74:77], v[146:149], v[138:141], v[74:77]
	v_mfma_f32_16x16x32_bf16 v[78:81], v[182:185], v[114:117], v[78:81]
	v_mfma_f32_16x16x32_bf16 v[82:85], v[182:185], v[138:141], v[82:85]
	v_mfma_f32_16x16x32_bf16 v[86:89], v[190:193], v[114:117], v[86:89]
	v_mfma_f32_16x16x32_bf16 v[90:93], v[190:193], v[138:141], v[90:93]
	v_mfma_f32_16x16x32_bf16 v[94:97], v[198:201], v[114:117], v[94:97]
	v_mfma_f32_16x16x32_bf16 v[98:101], v[198:201], v[138:141], v[98:101]
	s_setprio 0
	s_barrier
	s_mov_b32 m0, s31
	v_or_b32_e32 v238, 0x1c000, v131
	v_or_b32_e32 v246, 0x1c800, v131
	v_lshl_add_u64 v[8:9], v[8:9], 0, s[66:67]
	v_or_b32_e32 v242, 0x1c400, v131
	ds_read_b128 v[202:205], v238
	ds_read_b128 v[206:209], v242
	v_or_b32_e32 v131, 0x1cc00, v131
	ds_read_b128 v[210:213], v246
	ds_read_b128 v[214:217], v131
	global_load_lds_dwordx4 v[8:9], off
	v_lshl_add_u64 v[8:9], v[10:11], 0, s[66:67]
	s_mov_b32 m0, s30
	s_nop 0
	global_load_lds_dwordx4 v[8:9], off
	s_barrier
	s_waitcnt lgkmcnt(0)
	s_setprio 1
	s_waitcnt lgkmcnt(0)
	v_mfma_f32_16x16x32_bf16 v[8:11], v[142:145], v[202:205], v[118:121]
	v_mfma_f32_16x16x32_bf16 v[36:39], v[142:145], v[210:213], v[38:41]
	v_mfma_f32_16x16x32_bf16 v[40:43], v[150:153], v[202:205], v[42:45]
	v_mfma_f32_16x16x32_bf16 v[44:47], v[150:153], v[210:213], v[46:49]
	v_mfma_f32_16x16x32_bf16 v[48:51], v[186:189], v[202:205], v[50:53]
	v_mfma_f32_16x16x32_bf16 v[52:55], v[186:189], v[210:213], v[54:57]
	v_mfma_f32_16x16x32_bf16 v[56:59], v[194:197], v[202:205], v[58:61]
	v_mfma_f32_16x16x32_bf16 v[60:63], v[194:197], v[210:213], v[62:65]
	v_mfma_f32_16x16x32_bf16 v[8:11], v[146:149], v[206:209], v[8:11]
	v_mfma_f32_16x16x32_bf16 v[36:39], v[146:149], v[214:217], v[36:39]
	v_mfma_f32_16x16x32_bf16 v[40:43], v[182:185], v[206:209], v[40:43]
	v_mfma_f32_16x16x32_bf16 v[44:47], v[182:185], v[214:217], v[44:47]
	v_mfma_f32_16x16x32_bf16 v[48:51], v[190:193], v[206:209], v[48:51]
	v_mfma_f32_16x16x32_bf16 v[52:55], v[190:193], v[214:217], v[52:55]
	v_mfma_f32_16x16x32_bf16 v[56:59], v[198:201], v[206:209], v[56:59]
	v_mfma_f32_16x16x32_bf16 v[60:63], v[198:201], v[214:217], v[60:63]
	s_setprio 0
	s_mov_b32 m0, s28
	v_lshl_add_u64 v[6:7], v[6:7], 0, s[66:67]
	s_barrier
	ds_read_b128 v[118:121], v12 offset:49152
	ds_read_b128 v[142:145], v12 offset:50176
	ds_read_b128 v[146:149], v12 offset:51200
	ds_read_b128 v[150:153], v12 offset:52224
	ds_read_b128 v[182:185], v12 offset:53248
	ds_read_b128 v[186:189], v12 offset:54272
	ds_read_b128 v[190:193], v12 offset:55296
	ds_read_b128 v[194:197], v12 offset:56320
	global_load_lds_dwordx4 v[6:7], off
	v_lshl_add_u64 v[4:5], v[4:5], 0, s[66:67]
	s_mov_b32 m0, s27
	s_nop 0
	global_load_lds_dwordx4 v[4:5], off
	s_barrier
	s_waitcnt lgkmcnt(0)
	s_setprio 1
	s_waitcnt lgkmcnt(0)
	v_mfma_f32_16x16x32_bf16 v[4:7], v[118:121], v[110:113], v[154:157]
	v_mfma_f32_16x16x32_bf16 v[20:23], v[190:193], v[110:113], v[20:23]
	v_mfma_f32_16x16x32_bf16 v[24:27], v[190:193], v[134:137], v[24:27]
	v_mfma_f32_16x16x32_bf16 v[4:7], v[142:145], v[114:117], v[4:7]
	v_mfma_f32_16x16x32_bf16 v[154:157], v[118:121], v[134:137], v[158:161]
	v_mfma_f32_16x16x32_bf16 v[158:161], v[146:149], v[110:113], v[162:165]
	v_mfma_f32_16x16x32_bf16 v[162:165], v[146:149], v[134:137], v[166:169]
	v_mfma_f32_16x16x32_bf16 v[166:169], v[182:185], v[110:113], v[170:173]
	v_mfma_f32_16x16x32_bf16 v[170:173], v[182:185], v[134:137], v[174:177]
	v_mfma_f32_16x16x32_bf16 v[20:23], v[194:197], v[114:117], v[20:23]
	v_mfma_f32_16x16x32_bf16 v[24:27], v[194:197], v[138:141], v[24:27]
	v_mfma_f32_16x16x32_bf16 v[154:157], v[142:145], v[138:141], v[154:157]
	v_mfma_f32_16x16x32_bf16 v[158:161], v[150:153], v[114:117], v[158:161]
	v_mfma_f32_16x16x32_bf16 v[162:165], v[150:153], v[138:141], v[162:165]
	v_mfma_f32_16x16x32_bf16 v[166:169], v[186:189], v[114:117], v[166:169]
	v_mfma_f32_16x16x32_bf16 v[170:173], v[186:189], v[138:141], v[170:173]
	s_setprio 0
	s_barrier
	s_mov_b32 m0, s15
	v_lshl_add_u64 v[14:15], s[16:17], 0, v[0:1]
	global_load_lds_dwordx4 v[14:15], off
	v_lshl_add_u64 v[14:15], s[16:17], 0, v[2:3]
	s_mov_b32 m0, s2
	s_nop 0
	global_load_lds_dwordx4 v[14:15], off
	s_waitcnt vmcnt(6)
	s_barrier
	s_setprio 1
	v_mfma_f32_16x16x32_bf16 v[14:17], v[118:121], v[202:205], v[16:19]
	v_mfma_f32_16x16x32_bf16 v[28:31], v[118:121], v[210:213], v[28:31]
	v_mfma_f32_16x16x32_bf16 v[32:35], v[146:149], v[202:205], v[32:35]
	v_mfma_f32_16x16x32_bf16 v[64:67], v[146:149], v[210:213], v[66:69]
	v_mfma_f32_16x16x32_bf16 v[110:113], v[182:185], v[202:205], v[122:125]
	v_mfma_f32_16x16x32_bf16 v[114:117], v[182:185], v[210:213], v[126:129]
	v_mfma_f32_16x16x32_bf16 v[102:105], v[190:193], v[202:205], v[102:105]
	v_mfma_f32_16x16x32_bf16 v[106:109], v[190:193], v[210:213], v[106:109]
	v_mfma_f32_16x16x32_bf16 v[14:17], v[142:145], v[206:209], v[14:17]
	v_mfma_f32_16x16x32_bf16 v[28:31], v[142:145], v[214:217], v[28:31]
	v_mfma_f32_16x16x32_bf16 v[32:35], v[150:153], v[206:209], v[32:35]
	v_mfma_f32_16x16x32_bf16 v[64:67], v[150:153], v[214:217], v[64:67]
	v_mfma_f32_16x16x32_bf16 v[110:113], v[186:189], v[206:209], v[110:113]
	v_mfma_f32_16x16x32_bf16 v[114:117], v[186:189], v[214:217], v[114:117]
	v_mfma_f32_16x16x32_bf16 v[102:105], v[194:197], v[206:209], v[102:105]
	v_mfma_f32_16x16x32_bf16 v[106:109], v[194:197], v[214:217], v[106:109]
	s_setprio 0
	s_add_u32 s6, s6, 0x10180
	s_addc_u32 s7, s7, 0
	s_mov_b32 m0, s29
	v_lshl_add_u64 v[18:19], s[6:7], 0, v[0:1]
	s_barrier
	ds_read_b128 v[118:121], v133
	ds_read_b128 v[122:125], v178
	ds_read_b128 v[126:129], v179
	ds_read_b128 v[134:137], v221
	ds_read_b128 v[138:141], v12
	ds_read_b128 v[142:145], v12 offset:1024
	ds_read_b128 v[146:149], v12 offset:2048
	ds_read_b128 v[150:153], v12 offset:3072
	ds_read_b128 v[174:177], v12 offset:4096
	ds_read_b128 v[182:185], v12 offset:5120
	ds_read_b128 v[186:189], v12 offset:6144
	ds_read_b128 v[190:193], v12 offset:7168
	global_load_lds_dwordx4 v[18:19], off
	v_lshl_add_u64 v[2:3], s[6:7], 0, v[2:3]
	s_mov_b32 m0, s26
	s_nop 0
	global_load_lds_dwordx4 v[2:3], off
	s_barrier
	s_waitcnt lgkmcnt(0)
	s_setprio 1
	s_waitcnt lgkmcnt(0)
	v_mfma_f32_16x16x32_bf16 v[68:71], v[138:141], v[118:121], v[70:73]
	v_mfma_f32_16x16x32_bf16 v[72:75], v[138:141], v[126:129], v[74:77]
	v_mfma_f32_16x16x32_bf16 v[76:79], v[146:149], v[118:121], v[78:81]
	v_mfma_f32_16x16x32_bf16 v[80:83], v[146:149], v[126:129], v[82:85]
	v_mfma_f32_16x16x32_bf16 v[84:87], v[174:177], v[118:121], v[86:89]
	v_mfma_f32_16x16x32_bf16 v[88:91], v[174:177], v[126:129], v[90:93]
	v_mfma_f32_16x16x32_bf16 v[92:95], v[186:189], v[118:121], v[94:97]
	v_mfma_f32_16x16x32_bf16 v[96:99], v[186:189], v[126:129], v[98:101]
	v_mfma_f32_16x16x32_bf16 v[68:71], v[142:145], v[122:125], v[68:71]
	v_mfma_f32_16x16x32_bf16 v[72:75], v[142:145], v[134:137], v[72:75]
	v_mfma_f32_16x16x32_bf16 v[76:79], v[150:153], v[122:125], v[76:79]
	v_mfma_f32_16x16x32_bf16 v[80:83], v[150:153], v[134:137], v[80:83]
	v_mfma_f32_16x16x32_bf16 v[84:87], v[182:185], v[122:125], v[84:87]
	v_mfma_f32_16x16x32_bf16 v[88:91], v[182:185], v[134:137], v[88:91]
	v_mfma_f32_16x16x32_bf16 v[92:95], v[190:193], v[122:125], v[92:95]
	v_mfma_f32_16x16x32_bf16 v[96:99], v[190:193], v[134:137], v[96:99]
	s_setprio 0
	s_barrier
	ds_read_b128 v[194:197], v222
	ds_read_b128 v[198:201], v223
	ds_read_b128 v[202:205], v224
	ds_read_b128 v[206:209], v225
	s_barrier
	s_waitcnt lgkmcnt(0)
	s_setprio 1
	s_waitcnt lgkmcnt(3)
	v_mfma_f32_16x16x32_bf16 v[48:51], v[174:177], v[194:197], v[48:51]
	v_mfma_f32_16x16x32_bf16 v[8:11], v[138:141], v[194:197], v[8:11]
	s_waitcnt lgkmcnt(1)
	v_mfma_f32_16x16x32_bf16 v[36:39], v[138:141], v[202:205], v[36:39]
	v_mfma_f32_16x16x32_bf16 v[138:141], v[182:185], v[198:201], v[48:51]
	v_mfma_f32_16x16x32_bf16 v[48:51], v[174:177], v[202:205], v[52:55]
	v_mfma_f32_16x16x32_bf16 v[8:11], v[142:145], v[198:201], v[8:11]
	s_waitcnt lgkmcnt(0)
	v_mfma_f32_16x16x32_bf16 v[36:39], v[142:145], v[206:209], v[36:39]
	v_mfma_f32_16x16x32_bf16 v[40:43], v[146:149], v[194:197], v[40:43]
	v_mfma_f32_16x16x32_bf16 v[44:47], v[146:149], v[202:205], v[44:47]
	v_mfma_f32_16x16x32_bf16 v[142:145], v[182:185], v[206:209], v[48:51]
	v_mfma_f32_16x16x32_bf16 v[48:51], v[186:189], v[194:197], v[56:59]
	v_mfma_f32_16x16x32_bf16 v[40:43], v[150:153], v[198:201], v[40:43]
	v_mfma_f32_16x16x32_bf16 v[44:47], v[150:153], v[206:209], v[44:47]
	v_mfma_f32_16x16x32_bf16 v[146:149], v[190:193], v[198:201], v[48:51]
	v_mfma_f32_16x16x32_bf16 v[48:51], v[186:189], v[202:205], v[60:63]
	v_mfma_f32_16x16x32_bf16 v[150:153], v[190:193], v[206:209], v[48:51]
	s_setprio 0
	s_barrier
	s_nop 4
	ds_read_b128 v[48:51], v12 offset:16384
	ds_read_b128 v[52:55], v12 offset:17408
	ds_read_b128 v[56:59], v12 offset:18432
	ds_read_b128 v[60:63], v12 offset:19456
	ds_read_b128 v[174:177], v12 offset:20480
	ds_read_b128 v[182:185], v12 offset:21504
	ds_read_b128 v[186:189], v12 offset:22528
	ds_read_b128 v[190:193], v12 offset:23552
	s_waitcnt vmcnt(4)
	s_barrier
	s_waitcnt lgkmcnt(0)
	s_setprio 1
	s_waitcnt lgkmcnt(7)
	v_mfma_f32_16x16x32_bf16 v[2:5], v[48:51], v[118:121], v[4:7]
	s_waitcnt lgkmcnt(1)
	v_mfma_f32_16x16x32_bf16 v[18:21], v[186:189], v[118:121], v[20:23]
	v_mfma_f32_16x16x32_bf16 v[22:25], v[186:189], v[126:129], v[24:27]
	v_mfma_f32_16x16x32_bf16 v[2:5], v[52:55], v[122:125], v[2:5]
	v_mfma_f32_16x16x32_bf16 v[154:157], v[48:51], v[126:129], v[154:157]
	v_mfma_f32_16x16x32_bf16 v[158:161], v[56:59], v[118:121], v[158:161]
	v_mfma_f32_16x16x32_bf16 v[162:165], v[56:59], v[126:129], v[162:165]
	v_mfma_f32_16x16x32_bf16 v[166:169], v[174:177], v[118:121], v[166:169]
	v_mfma_f32_16x16x32_bf16 v[170:173], v[174:177], v[126:129], v[170:173]
	s_waitcnt lgkmcnt(0)
	v_mfma_f32_16x16x32_bf16 v[18:21], v[190:193], v[122:125], v[18:21]
	v_mfma_f32_16x16x32_bf16 v[22:25], v[190:193], v[134:137], v[22:25]
	v_mfma_f32_16x16x32_bf16 v[154:157], v[52:55], v[134:137], v[154:157]
	v_mfma_f32_16x16x32_bf16 v[158:161], v[60:63], v[122:125], v[158:161]
	v_mfma_f32_16x16x32_bf16 v[162:165], v[60:63], v[134:137], v[162:165]
	v_mfma_f32_16x16x32_bf16 v[166:169], v[182:185], v[122:125], v[166:169]
	v_mfma_f32_16x16x32_bf16 v[170:173], v[182:185], v[134:137], v[170:173]
	s_setprio 0
	s_setprio 1
	v_mfma_f32_16x16x32_bf16 v[26:29], v[48:51], v[202:205], v[28:31]
	v_mfma_f32_16x16x32_bf16 v[30:33], v[56:59], v[194:197], v[32:35]
	v_mfma_f32_16x16x32_bf16 v[134:137], v[60:63], v[198:201], v[30:33]
	v_mfma_f32_16x16x32_bf16 v[30:33], v[56:59], v[202:205], v[64:67]
	v_mfma_f32_16x16x32_bf16 v[210:213], v[60:63], v[206:209], v[30:33]
	v_mfma_f32_16x16x32_bf16 v[30:33], v[174:177], v[194:197], v[110:113]
	v_mfma_f32_16x16x32_bf16 v[214:217], v[182:185], v[198:201], v[30:33]
	v_mfma_f32_16x16x32_bf16 v[30:33], v[174:177], v[202:205], v[114:117]
	v_mfma_f32_16x16x32_bf16 v[14:17], v[48:51], v[194:197], v[14:17]
	v_mfma_f32_16x16x32_bf16 v[174:177], v[182:185], v[206:209], v[30:33]
	v_mfma_f32_16x16x32_bf16 v[30:33], v[186:189], v[194:197], v[102:105]
	v_mfma_f32_16x16x32_bf16 v[14:17], v[52:55], v[198:201], v[14:17]
	v_mfma_f32_16x16x32_bf16 v[26:29], v[52:55], v[206:209], v[26:29]
	v_mfma_f32_16x16x32_bf16 v[182:185], v[190:193], v[198:201], v[30:33]
	v_mfma_f32_16x16x32_bf16 v[30:33], v[186:189], v[202:205], v[106:109]
	v_mfma_f32_16x16x32_bf16 v[186:189], v[190:193], v[206:209], v[30:33]
	s_setprio 0
	s_barrier
	s_nop 4
	ds_read_b128 v[30:33], v13
	ds_read_b128 v[190:193], v226
	ds_read_b128 v[194:197], v227
	ds_read_b128 v[198:201], v228
	ds_read_b128 v[48:51], v12 offset:32768
	ds_read_b128 v[52:55], v12 offset:33792
	ds_read_b128 v[202:205], v12 offset:34816
	ds_read_b128 v[206:209], v12 offset:35840
	ds_read_b128 v[222:225], v12 offset:36864
	ds_read_b128 v[226:229], v12 offset:37888
	ds_read_b128 v[230:233], v12 offset:38912
	ds_read_b128 v[234:237], v12 offset:39936
	s_waitcnt vmcnt(2)
	s_barrier
	s_waitcnt lgkmcnt(0)
	s_setprio 1
	s_waitcnt lgkmcnt(7)
	v_mfma_f32_16x16x32_bf16 v[56:59], v[48:51], v[30:33], v[68:71]
	s_waitcnt lgkmcnt(6)
	v_mfma_f32_16x16x32_bf16 v[66:69], v[52:55], v[190:193], v[56:59]
	v_mfma_f32_16x16x32_bf16 v[56:59], v[48:51], v[194:197], v[72:75]
	v_mfma_f32_16x16x32_bf16 v[126:129], v[52:55], v[198:201], v[56:59]
	s_waitcnt lgkmcnt(5)
	v_mfma_f32_16x16x32_bf16 v[56:59], v[202:205], v[30:33], v[76:79]
	s_waitcnt lgkmcnt(4)
	v_mfma_f32_16x16x32_bf16 v[118:121], v[206:209], v[190:193], v[56:59]
	v_mfma_f32_16x16x32_bf16 v[56:59], v[202:205], v[194:197], v[80:83]
	v_mfma_f32_16x16x32_bf16 v[122:125], v[206:209], v[198:201], v[56:59]
	s_waitcnt lgkmcnt(3)
	v_mfma_f32_16x16x32_bf16 v[56:59], v[222:225], v[30:33], v[84:87]
	s_waitcnt lgkmcnt(2)
	v_mfma_f32_16x16x32_bf16 v[110:113], v[226:229], v[190:193], v[56:59]
	v_mfma_f32_16x16x32_bf16 v[56:59], v[222:225], v[194:197], v[88:91]
	v_mfma_f32_16x16x32_bf16 v[114:117], v[226:229], v[198:201], v[56:59]
	s_waitcnt lgkmcnt(1)
	v_mfma_f32_16x16x32_bf16 v[56:59], v[230:233], v[30:33], v[92:95]
	s_waitcnt lgkmcnt(0)
	v_mfma_f32_16x16x32_bf16 v[102:105], v[234:237], v[190:193], v[56:59]
	v_mfma_f32_16x16x32_bf16 v[56:59], v[230:233], v[194:197], v[96:99]
	v_mfma_f32_16x16x32_bf16 v[106:109], v[234:237], v[198:201], v[56:59]
	s_setprio 0
	s_barrier
	ds_read_b128 v[238:241], v238
	ds_read_b128 v[242:245], v242
	ds_read_b128 v[246:249], v246
	ds_read_b128 v[250:253], v131
	s_waitcnt vmcnt(0)
	s_barrier
	s_waitcnt lgkmcnt(0)
	s_setprio 1
	s_waitcnt lgkmcnt(3)
	v_mfma_f32_16x16x32_bf16 v[6:9], v[48:51], v[238:241], v[8:11]
	s_waitcnt lgkmcnt(2)
	v_mfma_f32_16x16x32_bf16 v[62:65], v[52:55], v[242:245], v[6:9]
	s_waitcnt lgkmcnt(1)
	v_mfma_f32_16x16x32_bf16 v[6:9], v[48:51], v[246:249], v[36:39]
	s_waitcnt lgkmcnt(0)
	v_mfma_f32_16x16x32_bf16 v[58:61], v[52:55], v[250:253], v[6:9]
	v_mfma_f32_16x16x32_bf16 v[6:9], v[202:205], v[238:241], v[40:43]
	v_mfma_f32_16x16x32_bf16 v[54:57], v[206:209], v[242:245], v[6:9]
	v_mfma_f32_16x16x32_bf16 v[6:9], v[202:205], v[246:249], v[44:47]
	v_mfma_f32_16x16x32_bf16 v[50:53], v[206:209], v[250:253], v[6:9]
	v_mfma_f32_16x16x32_bf16 v[6:9], v[222:225], v[238:241], v[138:141]
	v_mfma_f32_16x16x32_bf16 v[46:49], v[226:229], v[242:245], v[6:9]
	v_mfma_f32_16x16x32_bf16 v[6:9], v[222:225], v[246:249], v[142:145]
	v_mfma_f32_16x16x32_bf16 v[42:45], v[226:229], v[250:253], v[6:9]
	v_mfma_f32_16x16x32_bf16 v[6:9], v[230:233], v[238:241], v[146:149]
	v_mfma_f32_16x16x32_bf16 v[38:41], v[234:237], v[242:245], v[6:9]
	v_mfma_f32_16x16x32_bf16 v[6:9], v[230:233], v[246:249], v[150:153]
	v_mfma_f32_16x16x32_bf16 v[34:37], v[234:237], v[250:253], v[6:9]
	s_setprio 0
	s_barrier
	s_nop 4
	ds_read_b128 v[6:9], v12 offset:49152
	ds_read_b128 v[138:141], v12 offset:50176
	ds_read_b128 v[142:145], v12 offset:51200
	ds_read_b128 v[146:149], v12 offset:52224
	ds_read_b128 v[150:153], v12 offset:53248
	ds_read_b128 v[202:205], v12 offset:54272
	ds_read_b128 v[206:209], v12 offset:55296
	ds_read_b128 v[222:225], v12 offset:56320
	s_barrier
	s_waitcnt lgkmcnt(0)
	s_setprio 1
	s_waitcnt lgkmcnt(7)
	v_mfma_f32_16x16x32_bf16 v[2:5], v[6:9], v[30:33], v[2:5]
	s_waitcnt lgkmcnt(6)
	v_mfma_f32_16x16x32_bf16 v[94:97], v[138:141], v[190:193], v[2:5]
	v_mfma_f32_16x16x32_bf16 v[2:5], v[6:9], v[194:197], v[154:157]
	v_mfma_f32_16x16x32_bf16 v[98:101], v[138:141], v[198:201], v[2:5]
	s_waitcnt lgkmcnt(5)
	v_mfma_f32_16x16x32_bf16 v[2:5], v[142:145], v[30:33], v[158:161]
	s_waitcnt lgkmcnt(4)
	v_mfma_f32_16x16x32_bf16 v[86:89], v[146:149], v[190:193], v[2:5]
	v_mfma_f32_16x16x32_bf16 v[2:5], v[142:145], v[194:197], v[162:165]
	v_mfma_f32_16x16x32_bf16 v[90:93], v[146:149], v[198:201], v[2:5]
	s_waitcnt lgkmcnt(3)
	v_mfma_f32_16x16x32_bf16 v[2:5], v[150:153], v[30:33], v[166:169]
	s_waitcnt lgkmcnt(2)
	v_mfma_f32_16x16x32_bf16 v[78:81], v[202:205], v[190:193], v[2:5]
	v_mfma_f32_16x16x32_bf16 v[2:5], v[150:153], v[194:197], v[170:173]
	v_mfma_f32_16x16x32_bf16 v[82:85], v[202:205], v[198:201], v[2:5]
	s_waitcnt lgkmcnt(1)
	v_mfma_f32_16x16x32_bf16 v[2:5], v[206:209], v[30:33], v[18:21]
	s_waitcnt lgkmcnt(0)
	v_mfma_f32_16x16x32_bf16 v[70:73], v[222:225], v[190:193], v[2:5]
	v_mfma_f32_16x16x32_bf16 v[2:5], v[206:209], v[194:197], v[22:25]
	v_mfma_f32_16x16x32_bf16 v[74:77], v[222:225], v[198:201], v[2:5]
	s_setprio 0
	s_setprio 1
	v_mfma_f32_16x16x32_bf16 v[2:5], v[6:9], v[238:241], v[14:17]
	v_mfma_f32_16x16x32_bf16 v[30:33], v[138:141], v[242:245], v[2:5]
	v_mfma_f32_16x16x32_bf16 v[2:5], v[6:9], v[246:249], v[26:29]
	v_mfma_f32_16x16x32_bf16 v[26:29], v[138:141], v[250:253], v[2:5]
	v_mfma_f32_16x16x32_bf16 v[2:5], v[142:145], v[238:241], v[134:137]
	v_mfma_f32_16x16x32_bf16 v[22:25], v[146:149], v[242:245], v[2:5]
	v_mfma_f32_16x16x32_bf16 v[2:5], v[142:145], v[246:249], v[210:213]
	v_mfma_f32_16x16x32_bf16 v[18:21], v[146:149], v[250:253], v[2:5]
	v_mfma_f32_16x16x32_bf16 v[2:5], v[150:153], v[238:241], v[214:217]
	v_mfma_f32_16x16x32_bf16 v[14:17], v[202:205], v[242:245], v[2:5]
	v_mfma_f32_16x16x32_bf16 v[2:5], v[150:153], v[246:249], v[174:177]
	v_mfma_f32_16x16x32_bf16 v[10:13], v[202:205], v[250:253], v[2:5]
	v_mfma_f32_16x16x32_bf16 v[2:5], v[206:209], v[238:241], v[182:185]
	v_mfma_f32_16x16x32_bf16 v[6:9], v[222:225], v[242:245], v[2:5]
	v_mfma_f32_16x16x32_bf16 v[2:5], v[206:209], v[246:249], v[186:189]
	v_mfma_f32_16x16x32_bf16 v[2:5], v[222:225], v[250:253], v[2:5]
	s_setprio 0
	v_cmp_gt_u32_e32 vcc, s37, v130
	s_barrier
	s_and_saveexec_b64 s[6:7], vcc
	s_cbranch_execz .LBB0_1095
	s_barrier
